# attention tile bodies: ds_read_b128 K/V fragment loads hoisted into free VGPR quads with counted lgkmcnt waits (on top of rcp division rewrite)
# baseline (speedup 1.0000x reference)
; #define MFMA32(a, b, c) __builtin_amdgcn_mfma_f32_32x32x16_bf16((a), (b), (c), 0, 0, 0)
; template <int DQK, bool WIN>
; DI void attn_item(const u16* __restrict__ Qb, int ldq, const u16* __restrict__ Kb, int ldk, const u16* __restrict__ Vtb, int qb,
;                   float qscale, float sink2, const u16* __restrict__ zb, int ldz, u16* __restrict__ ob, int ldo, u16* lds) {
;     ...
;       for (int kb = 0; kb < 2; ++kb) {
; #pragma unroll
;         for (int i = 0; i < 16; ++i) st[kb][i] = 0.f;
; #pragma unroll
;         for (int s = 0; s < NKS; ++s) {
;           bf16x8 a = *(const bf16x8*)(ks + (kb * 32 + r) * KST + 16 * s + 8 * hh);
;           st[kb] = MFMA32(a, qf[s], st[kb]);
;         }
;       }
;       float mx = -INFINITY;
; #pragma unroll
;       for (int kb = 0; kb < 2; ++kb)
; #pragma unroll
;         for (int i = 0; i < 16; ++i) {
;           float v = st[kb][i];
;           if (MASK) {
;             int kg = k0 + kb * 32 + (i & 3) + 8 * (i >> 2) + 4 * hh;
;             bool ok = kg <= qrow;
;             if (WIN) ok = ok && (qrow - kg < 128);
;             v = ok ? v : -INFINITY;
;             st[kb][i] = v;
;           }
;           mx = fmaxf(mx, v);
;         }
.LBB0_233:
	s_add_i32 s0, s31, -1
	s_add_i32 s1, s20, 0xffffff40
	s_cmp_lt_u32 s0, s29
	v_cmp_le_i32_e64 s[8:9], s1, v154
	s_mov_b64 s[24:25], -1
	s_cbranch_scc1 .LBB0_239
	v_mov_b64_e32 v[64:65], v[16:17]
	v_mov_b64_e32 v[48:49], v[32:33]
	v_mov_b32_e32 v158, v157
	v_mov_b32_e32 v0, v142
	v_mov_b64_e32 v[62:63], v[14:15]
	v_mov_b64_e32 v[60:61], v[12:13]
	v_mov_b64_e32 v[58:59], v[10:11]
	v_mov_b64_e32 v[56:57], v[8:9]
	v_mov_b64_e32 v[54:55], v[6:7]
	v_mov_b64_e32 v[52:53], v[4:5]
	v_mov_b64_e32 v[50:51], v[2:3]
	v_mov_b64_e32 v[46:47], v[30:31]
	v_mov_b64_e32 v[44:45], v[28:29]
	v_mov_b64_e32 v[42:43], v[26:27]
	v_mov_b64_e32 v[40:41], v[24:25]
	v_mov_b64_e32 v[38:39], v[22:23]
	v_mov_b64_e32 v[36:37], v[20:21]
	v_mov_b64_e32 v[34:35], v[18:19]
	s_and_saveexec_b64 s[24:25], s[8:9]
	s_cbranch_execz .LBB0_238
	ds_read_b128 v[220:223], v155
	ds_read_b128 v[224:227], v155 offset:32
	ds_read_b128 v[228:231], v155 offset:64
	ds_read_b128 v[232:235], v155 offset:6688
	ds_read_b128 v[236:239], v155 offset:96
	ds_read_b128 v[240:243], v155 offset:128
	ds_read_b128 v[244:247], v155 offset:160
	ds_read_b128 v[248:251], v155 offset:6656
	v_mov_b32_e32 v196, v142
	s_waitcnt lgkmcnt(7)
	v_mfma_f32_32x32x16_bf16 v[50:65], v[220:223], v[66:69], 0
	ds_read_b128 v[220:223], v155 offset:6720
	s_waitcnt lgkmcnt(7)
	v_mfma_f32_32x32x16_bf16 v[50:65], v[224:227], v[70:73], v[50:65]
	ds_read_b128 v[224:227], v155 offset:6752
	s_waitcnt lgkmcnt(7)
	v_mfma_f32_32x32x16_bf16 v[50:65], v[228:231], v[74:77], v[50:65]
	ds_read_b128 v[228:231], v155 offset:6784
	s_waitcnt lgkmcnt(6)
	v_mfma_f32_32x32x16_bf16 v[50:65], v[236:239], v[78:81], v[50:65]
	ds_read_b128 v[236:239], v155 offset:6816
	s_waitcnt lgkmcnt(6)
	v_mfma_f32_32x32x16_bf16 v[50:65], v[240:243], v[82:85], v[50:65]
	s_waitcnt lgkmcnt(5)
	v_mfma_f32_32x32x16_bf16 v[50:65], v[244:247], v[86:89], v[50:65]
	s_waitcnt lgkmcnt(4)
	v_mfma_f32_32x32x16_bf16 v[34:49], v[248:251], v[66:69], 0
	v_mfma_f32_32x32x16_bf16 v[34:49], v[232:235], v[70:73], v[34:49]
	s_waitcnt lgkmcnt(3)
	v_mfma_f32_32x32x16_bf16 v[34:49], v[220:223], v[74:77], v[34:49]
	s_waitcnt lgkmcnt(2)
	v_mfma_f32_32x32x16_bf16 v[34:49], v[224:227], v[78:81], v[34:49]
	s_waitcnt lgkmcnt(1)
	v_mfma_f32_32x32x16_bf16 v[34:49], v[228:231], v[82:85], v[34:49]
	s_waitcnt lgkmcnt(0)
	v_mfma_f32_32x32x16_bf16 v[34:49], v[236:239], v[86:89], v[34:49]
	v_add_u32_e32 v158, s20, v146
	v_add_u32_e32 v0, 0xffffff40, v158
	v_cmp_le_i32_e32 vcc, v0, v130
	s_nop 1
	v_cndmask_b32_e32 v159, v176, v50, vcc
	v_cmp_lt_i32_e32 vcc, v0, v130
	s_nop 1
	v_cndmask_b32_e32 v0, v176, v51, vcc
	v_add_u32_e32 v51, 0xffffff42, v158
	v_cmp_le_i32_e32 vcc, v51, v130
	v_add_u32_e32 v51, 0xffffff43, v158
	v_max3_f32 v50, v159, s94, v0
	v_cndmask_b32_e32 v161, v176, v52, vcc
	v_cmp_le_i32_e32 vcc, v51, v130
	v_add_u32_e32 v51, 0xffffff48, v158
	s_nop 0
	v_cndmask_b32_e32 v160, v176, v53, vcc
	v_cmp_le_i32_e32 vcc, v51, v130
	v_add_u32_e32 v51, 0xffffff49, v158
	v_max3_f32 v50, v50, v161, v160
	v_cndmask_b32_e32 v164, v176, v54, vcc
	v_cmp_le_i32_e32 vcc, v51, v130
	v_add_u32_e32 v51, 0xffffff4a, v158
	s_nop 0
	v_cndmask_b32_e32 v162, v176, v55, vcc
	v_cmp_le_i32_e32 vcc, v51, v130
	v_add_u32_e32 v51, 0xffffff4b, v158
	v_max3_f32 v50, v50, v164, v162
	v_cndmask_b32_e32 v165, v176, v56, vcc
	v_cmp_le_i32_e32 vcc, v51, v130
	v_add_u32_e32 v51, 0xffffff50, v158
	s_nop 0
	v_cndmask_b32_e32 v166, v176, v57, vcc
	v_cmp_le_i32_e32 vcc, v51, v130
	v_add_u32_e32 v51, 0xffffff51, v158
	v_max3_f32 v50, v50, v165, v166
	v_cndmask_b32_e32 v205, v176, v58, vcc
	v_cmp_le_i32_e32 vcc, v51, v130
	v_add_u32_e32 v51, 0xffffff52, v158
	s_nop 0
	v_cndmask_b32_e32 v203, v176, v59, vcc
	v_cmp_le_i32_e32 vcc, v51, v130
	v_add_u32_e32 v51, 0xffffff53, v158
	v_max3_f32 v50, v50, v205, v203
	v_cndmask_b32_e32 v204, v176, v60, vcc
	v_cmp_le_i32_e32 vcc, v51, v130
	v_add_u32_e32 v51, 0xffffff58, v158
	s_nop 0
	v_cndmask_b32_e32 v201, v176, v61, vcc
	v_cmp_le_i32_e32 vcc, v51, v130
	v_add_u32_e32 v51, 0xffffff59, v158
	v_max3_f32 v50, v50, v204, v201
	v_cndmask_b32_e32 v202, v176, v62, vcc
	v_cmp_le_i32_e32 vcc, v51, v130
	v_add_u32_e32 v51, 0xffffff5a, v158
	s_nop 0
	v_cndmask_b32_e32 v199, v176, v63, vcc
	v_cmp_le_i32_e32 vcc, v51, v130
	v_add_u32_e32 v51, 0xffffff5b, v158
	v_max3_f32 v50, v50, v202, v199
	v_cndmask_b32_e32 v200, v176, v64, vcc
	v_cmp_le_i32_e32 vcc, v51, v130
	v_add_u32_e32 v51, 0xffffff60, v158
	s_nop 0
	v_cndmask_b32_e32 v197, v176, v65, vcc
	v_cmp_le_i32_e32 vcc, v51, v130
	v_max3_f32 v50, v50, v200, v197
	s_nop 0
	v_cndmask_b32_e32 v198, v176, v34, vcc
	v_add_u32_e32 v34, 0xffffff61, v158
	v_cmp_le_i32_e32 vcc, v34, v130
	s_nop 1
	v_cndmask_b32_e32 v195, v176, v35, vcc
	v_add_u32_e32 v35, 0xffffff62, v158
	v_cmp_le_i32_e32 vcc, v35, v130
	v_add_u32_e32 v35, 0xffffff63, v158
	v_max3_f32 v34, v50, v198, v195
	v_cndmask_b32_e32 v194, v176, v36, vcc
	v_cmp_le_i32_e32 vcc, v35, v130
	v_add_u32_e32 v35, 0xffffff68, v158
	v_and_b32_e32 v36, 64, v172
	v_cndmask_b32_e32 v193, v176, v37, vcc
	v_cmp_le_i32_e32 vcc, v35, v130
	v_add_u32_e32 v35, 0xffffff69, v158
	v_max3_f32 v34, v34, v194, v193
	v_cndmask_b32_e32 v192, v176, v38, vcc
	v_cmp_le_i32_e32 vcc, v35, v130
	v_add_u32_e32 v35, 0xffffff6a, v158
	v_add_u32_e32 v36, 64, v36
	v_cndmask_b32_e32 v167, v176, v39, vcc
	v_cmp_le_i32_e32 vcc, v35, v130
	v_add_u32_e32 v35, 0xffffff6b, v158
	v_max3_f32 v34, v34, v192, v167
	v_cndmask_b32_e32 v182, v176, v40, vcc
	v_cmp_le_i32_e32 vcc, v35, v130
	v_add_u32_e32 v35, 0xffffff70, v158
	v_mov_b64_e32 v[64:65], v[16:17]
	v_cndmask_b32_e32 v183, v176, v41, vcc
	v_cmp_le_i32_e32 vcc, v35, v130
	v_add_u32_e32 v35, 0xffffff71, v158
	v_max3_f32 v34, v34, v182, v183
	v_cndmask_b32_e32 v184, v176, v42, vcc
	v_cmp_le_i32_e32 vcc, v35, v130
	v_add_u32_e32 v35, 0xffffff72, v158
	v_mov_b64_e32 v[62:63], v[14:15]
	v_cndmask_b32_e32 v185, v176, v43, vcc
	v_cmp_le_i32_e32 vcc, v35, v130
	v_add_u32_e32 v35, 0xffffff73, v158
	v_max3_f32 v34, v34, v184, v185
	v_cndmask_b32_e32 v186, v176, v44, vcc
	v_cmp_le_i32_e32 vcc, v35, v130
	v_add_u32_e32 v35, 0xffffff78, v158
	v_mov_b64_e32 v[60:61], v[12:13]
	v_cndmask_b32_e32 v187, v176, v45, vcc
	v_cmp_le_i32_e32 vcc, v35, v130
	v_add_u32_e32 v35, 0xffffff79, v158
	v_max3_f32 v34, v34, v186, v187
	v_cndmask_b32_e32 v188, v176, v46, vcc
	v_cmp_le_i32_e32 vcc, v35, v130
	v_add_u32_e32 v35, 0xffffff7a, v158
	v_mov_b64_e32 v[58:59], v[10:11]
	v_cndmask_b32_e32 v189, v176, v47, vcc
	v_cmp_le_i32_e32 vcc, v35, v130
	v_add_u32_e32 v35, 0xffffff7b, v158
	v_max3_f32 v34, v34, v188, v189
	v_cndmask_b32_e32 v190, v176, v48, vcc
	v_cmp_le_i32_e32 vcc, v35, v130
	v_xor_b32_e32 v35, 32, v172
	v_mov_b64_e32 v[56:57], v[8:9]
	v_cndmask_b32_e32 v191, v176, v49, vcc
	v_cmp_lt_i32_e32 vcc, v35, v36
	v_max3_f32 v34, v34, v190, v191
	v_mov_b64_e32 v[54:55], v[6:7]
	v_cndmask_b32_e32 v35, v172, v35, vcc
	v_lshlrev_b32_e32 v35, 2, v35
	ds_bpermute_b32 v35, v35, v34
	v_mov_b64_e32 v[52:53], v[4:5]
	v_mov_b64_e32 v[50:51], v[2:3]
	s_waitcnt lgkmcnt(0)
; DI unsigned pack2(float a, float b) { unsigned r; asm("v_cvt_pk_bf16_f32 %0, %1, %2\n\ts_nop 1" : "=v"(r) : "v"(a), "v"(b)); return r; }
; #define MFMA32(a, b, c) __builtin_amdgcn_mfma_f32_32x32x16_bf16((a), (b), (c), 0, 0, 0)
; template <int DQK, bool WIN>
; DI void attn_item(const u16* __restrict__ Qb, int ldq, const u16* __restrict__ Kb, int ldk, const u16* __restrict__ Vtb, int qb,
;                   float qscale, float sink2, const u16* __restrict__ zb, int ldz, u16* __restrict__ ob, int ldo, u16* lds) {
;     ...
;       mx = fmaxf(mx, __shfl_xor(mx, 32));
;       const float mn = fmaxf(m, mx);
;       if (__any(mn != m)) {
;         const float alpha = __builtin_amdgcn_exp2f((m - mn) * qscale);
;         lsum *= alpha;
; #pragma unroll
;         for (int i = 0; i < 16; ++i) { o[0][i] *= alpha; o[1][i] *= alpha; }
;       }
;       m = mn;
;       const float nb = -mn * qscale;
;       float ps = 0.f;
; #pragma unroll
;       for (int kb = 0; kb < 2; ++kb)
; #pragma unroll
;         for (int i = 0; i < 16; ++i) { float pv = __builtin_amdgcn_exp2f(fmaf(st[kb][i], qscale, nb)); st[kb][i] = pv; ps += pv; }
;       lsum += ps;
; #pragma unroll
;       for (int kb = 0; kb < 2; ++kb)
; #pragma unroll
;         for (int s2 = 0; s2 < 2; ++s2) {
;           union { bf16x8 v; unsigned u[4]; } pf;
; #pragma unroll
;           for (int j = 0; j < 4; ++j) pf.u[j] = pack2(st[kb][8 * s2 + 2 * j], st[kb][8 * s2 + 2 * j + 1]);
; #pragma unroll
;           for (int vb = 0; vb < 2; ++vb) {
;             const bf16x8 vf = *(const bf16x8*)(vs + (vb * 32 + r) * 72 + (kb * 2 + s2) * 16 + hh * 8);
;             o[vb] = MFMA32(vf, pf.v, o[vb]);
;           }
;         }
	v_max3_f32 v158, v157, v34, v35
	v_mov_b64_e32 v[48:49], v[32:33]
	v_cmp_neq_f32_e32 vcc, v158, v157
	v_mov_b64_e32 v[46:47], v[30:31]
	v_mov_b64_e32 v[44:45], v[28:29]
	v_mov_b64_e32 v[42:43], v[26:27]
	v_mov_b64_e32 v[40:41], v[24:25]
	v_mov_b64_e32 v[38:39], v[22:23]
	v_mov_b64_e32 v[36:37], v[20:21]
	v_mov_b64_e32 v[34:35], v[18:19]
	s_cbranch_vccz .LBB0_237
	v_sub_f32_e32 v34, v157, v158
	v_mul_f32_e32 v34, 0x3e16c740, v34
	v_exp_f32_e32 v50, v34
	s_nop 0
	v_mul_f32_e32 v196, v142, v50
	v_pk_mul_f32 v[48:49], v[32:33], v[50:51] op_sel_hi:[1,0]
	v_pk_mul_f32 v[46:47], v[30:31], v[50:51] op_sel_hi:[1,0]
	v_pk_mul_f32 v[44:45], v[28:29], v[50:51] op_sel_hi:[1,0]
	v_pk_mul_f32 v[42:43], v[26:27], v[50:51] op_sel_hi:[1,0]
	v_pk_mul_f32 v[40:41], v[24:25], v[50:51] op_sel_hi:[1,0]
	v_pk_mul_f32 v[38:39], v[22:23], v[50:51] op_sel_hi:[1,0]
	v_pk_mul_f32 v[36:37], v[20:21], v[50:51] op_sel_hi:[1,0]
	v_pk_mul_f32 v[34:35], v[18:19], v[50:51] op_sel_hi:[1,0]
	v_pk_mul_f32 v[64:65], v[16:17], v[50:51] op_sel_hi:[1,0]
	v_pk_mul_f32 v[62:63], v[14:15], v[50:51] op_sel_hi:[1,0]
	v_pk_mul_f32 v[60:61], v[12:13], v[50:51] op_sel_hi:[1,0]
	v_pk_mul_f32 v[58:59], v[10:11], v[50:51] op_sel_hi:[1,0]
	v_pk_mul_f32 v[56:57], v[8:9], v[50:51] op_sel_hi:[1,0]
	v_pk_mul_f32 v[54:55], v[6:7], v[50:51] op_sel_hi:[1,0]
	v_pk_mul_f32 v[52:53], v[4:5], v[50:51] op_sel_hi:[1,0]
	v_pk_mul_f32 v[50:51], v[2:3], v[50:51] op_sel_hi:[1,0]
.LBB0_237:
	ds_read_b128 v[220:223], v156 offset:13312
	ds_read_b128 v[224:227], v156 offset:17920
	ds_read_b128 v[228:231], v156 offset:17952
	ds_read_b128 v[232:235], v156 offset:13376
	ds_read_b128 v[236:239], v156 offset:17984
	ds_read_b128 v[240:243], v156 offset:13408
	v_mul_f32_e32 v206, 0xbe16c740, v158
	v_fmamk_f32 v159, v159, 0x3e16c740, v206
	v_exp_f32_e32 v159, v159
	v_fmamk_f32 v0, v0, 0x3e16c740, v206
	v_exp_f32_e32 v208, v0
	v_fmamk_f32 v164, v164, 0x3e16c740, v206
	v_add_f32_e32 v207, 0, v159
	v_fmamk_f32 v161, v161, 0x3e16c740, v206
	v_add_f32_e32 v0, v208, v207
	v_exp_f32_e32 v207, v164
	v_fmamk_f32 v164, v165, 0x3e16c740, v206
	v_exp_f32_e32 v209, v164
	v_fmamk_f32 v164, v166, 0x3e16c740, v206
	v_exp_f32_e32 v210, v164
	v_fmamk_f32 v164, v205, 0x3e16c740, v206
	v_exp_f32_e32 v205, v164
	v_fmamk_f32 v164, v203, 0x3e16c740, v206
	v_exp_f32_e32 v203, v164
	v_fmamk_f32 v164, v204, 0x3e16c740, v206
	v_exp_f32_e32 v204, v164
	v_fmamk_f32 v164, v201, 0x3e16c740, v206
	v_exp_f32_e32 v201, v164
	v_fmamk_f32 v164, v202, 0x3e16c740, v206
	v_exp_f32_e32 v202, v164
	v_fmamk_f32 v164, v199, 0x3e16c740, v206
	v_exp_f32_e32 v199, v164
	v_fmamk_f32 v164, v200, 0x3e16c740, v206
	v_exp_f32_e32 v200, v164
	v_fmamk_f32 v164, v197, 0x3e16c740, v206
	v_exp_f32_e32 v197, v164
	v_fmamk_f32 v164, v198, 0x3e16c740, v206
	v_exp_f32_e32 v198, v164
	v_fmamk_f32 v164, v195, 0x3e16c740, v206
	v_exp_f32_e32 v195, v164
	v_fmamk_f32 v164, v194, 0x3e16c740, v206
	v_exp_f32_e32 v194, v164
	v_fmamk_f32 v164, v193, 0x3e16c740, v206
	v_exp_f32_e32 v193, v164
	v_fmamk_f32 v164, v192, 0x3e16c740, v206
	v_exp_f32_e32 v192, v164
	v_fmamk_f32 v164, v167, 0x3e16c740, v206
	v_exp_f32_e32 v211, v164
	v_fmamk_f32 v164, v182, 0x3e16c740, v206
	v_exp_f32_e32 v212, v164
	v_fmamk_f32 v164, v183, 0x3e16c740, v206
	v_exp_f32_e32 v213, v164
	v_fmamk_f32 v164, v184, 0x3e16c740, v206
	v_exp_f32_e32 v214, v164
	v_fmamk_f32 v164, v185, 0x3e16c740, v206
	v_exp_f32_e32 v215, v164
	v_fmamk_f32 v164, v186, 0x3e16c740, v206
	v_exp_f32_e32 v216, v164
	v_fmamk_f32 v164, v187, 0x3e16c740, v206
	v_exp_f32_e32 v217, v164
	v_fmamk_f32 v164, v188, 0x3e16c740, v206
	v_exp_f32_e32 v218, v164
	v_fmamk_f32 v164, v189, 0x3e16c740, v206
	ds_read_b128 v[186:189], v156 offset:13344
	v_fmamk_f32 v160, v160, 0x3e16c740, v206
	v_fmamk_f32 v162, v162, 0x3e16c740, v206
	v_exp_f32_e32 v219, v164
	v_fmamk_f32 v164, v190, 0x3e16c740, v206
	v_exp_f32_e32 v161, v161
	v_exp_f32_e32 v160, v160
	v_exp_f32_e32 v162, v162
	v_exp_f32_e32 v190, v164
	v_cvt_pk_bf16_f32 v164, v159, v208
	s_nop 1
	v_cvt_pk_bf16_f32 v165, v161, v160
	s_nop 1
	v_cvt_pk_bf16_f32 v166, v207, v162
	s_nop 1
	v_cvt_pk_bf16_f32 v167, v209, v210
	s_nop 1
	v_add_f32_e32 v0, v161, v0
	s_waitcnt lgkmcnt(6)
	v_mfma_f32_32x32x16_bf16 v[34:49], v[220:223], v[164:167], v[34:49]
	v_add_f32_e32 v0, v160, v0
	v_add_f32_e32 v0, v207, v0
	v_add_f32_e32 v0, v162, v0
	v_add_f32_e32 v0, v209, v0
	v_add_f32_e32 v0, v210, v0
	v_add_f32_e32 v0, v205, v0
	s_waitcnt lgkmcnt(0)
	v_mfma_f32_32x32x16_bf16 v[50:65], v[224:227], v[164:167], v[50:65]
	v_cvt_pk_bf16_f32 v164, v205, v203
	s_nop 1
	v_cvt_pk_bf16_f32 v165, v204, v201
	s_nop 1
	v_cvt_pk_bf16_f32 v166, v202, v199
	s_nop 1
	v_cvt_pk_bf16_f32 v167, v200, v197
	s_nop 1
	v_add_f32_e32 v0, v203, v0
	v_add_f32_e32 v0, v204, v0
	s_waitcnt lgkmcnt(0)
	v_mfma_f32_32x32x16_bf16 v[50:65], v[228:231], v[164:167], v[50:65]
	v_add_f32_e32 v0, v201, v0
	v_add_f32_e32 v0, v202, v0
	v_add_f32_e32 v0, v199, v0
	v_add_f32_e32 v0, v200, v0
	v_add_f32_e32 v0, v197, v0
	v_fmac_f32_e32 v206, 0x3e16c740, v191
	v_mfma_f32_32x32x16_bf16 v[34:49], v[186:189], v[164:167], v[34:49]
	v_cvt_pk_bf16_f32 v164, v198, v195
	s_nop 1
	v_cvt_pk_bf16_f32 v165, v194, v193
	s_nop 1
	v_cvt_pk_bf16_f32 v166, v192, v211
	s_nop 1
	v_cvt_pk_bf16_f32 v167, v212, v213
	s_nop 1
	v_add_f32_e32 v0, v198, v0
	v_exp_f32_e32 v191, v206
	v_add_f32_e32 v0, v195, v0
	s_waitcnt lgkmcnt(0)
	v_mfma_f32_32x32x16_bf16 v[34:49], v[232:235], v[164:167], v[34:49]
	v_add_f32_e32 v0, v194, v0
	v_add_f32_e32 v0, v193, v0
	v_add_f32_e32 v0, v192, v0
	v_add_f32_e32 v0, v211, v0
	v_add_f32_e32 v0, v212, v0
	v_add_f32_e32 v0, v213, v0
	s_waitcnt lgkmcnt(0)
	v_mfma_f32_32x32x16_bf16 v[50:65], v[236:239], v[164:167], v[50:65]
	v_cvt_pk_bf16_f32 v164, v214, v215
	s_nop 1
	v_cvt_pk_bf16_f32 v165, v216, v217
	s_nop 1
	v_cvt_pk_bf16_f32 v166, v218, v219
	s_nop 1
	v_cvt_pk_bf16_f32 v167, v190, v191
	s_nop 1
	v_add_f32_e32 v0, v214, v0
	v_add_f32_e32 v0, v215, v0
	s_waitcnt lgkmcnt(0)
	v_mfma_f32_32x32x16_bf16 v[34:49], v[240:243], v[164:167], v[34:49]
	ds_read_b128 v[182:185], v156 offset:18016
	v_add_f32_e32 v0, v216, v0
	v_add_f32_e32 v0, v217, v0
	v_add_f32_e32 v0, v218, v0
	v_add_f32_e32 v0, v219, v0
	v_add_f32_e32 v0, v190, v0
	v_add_f32_e32 v0, v191, v0
	s_waitcnt lgkmcnt(0)
	v_mfma_f32_32x32x16_bf16 v[50:65], v[182:185], v[164:167], v[50:65]
	v_add_f32_e32 v0, v0, v196

; #define MFMA32(a, b, c) __builtin_amdgcn_mfma_f32_32x32x16_bf16((a), (b), (c), 0, 0, 0)
; template <int DQK, bool WIN>
; DI void attn_item(const u16* __restrict__ Qb, int ldq, const u16* __restrict__ Kb, int ldk, const u16* __restrict__ Vtb, int qb,
;                   float qscale, float sink2, const u16* __restrict__ zb, int ldz, u16* __restrict__ ob, int ldo, u16* lds) {
;     ...
;       for (int kb = 0; kb < 2; ++kb) {
; #pragma unroll
;         for (int i = 0; i < 16; ++i) st[kb][i] = 0.f;
; #pragma unroll
;         for (int s = 0; s < NKS; ++s) {
;           bf16x8 a = *(const bf16x8*)(ks + (kb * 32 + r) * KST + 16 * s + 8 * hh);
;           st[kb] = MFMA32(a, qf[s], st[kb]);
;         }
;       }
;       float mx = -INFINITY;
; #pragma unroll
;       for (int kb = 0; kb < 2; ++kb)
; #pragma unroll
;         for (int i = 0; i < 16; ++i) {
;           float v = st[kb][i];
;           if (MASK) {
;             int kg = k0 + kb * 32 + (i & 3) + 8 * (i >> 2) + 4 * hh;
;             bool ok = kg <= qrow;
;             if (WIN) ok = ok && (qrow - kg < 128);
;             v = ok ? v : -INFINITY;
;             st[kb][i] = v;
;           }
;           mx = fmaxf(mx, v);
;         }
;       mx = fmaxf(mx, __shfl_xor(mx, 32));
;       const float mn = fmaxf(m, mx);
;       if (__any(mn != m)) {
;         const float alpha = __builtin_amdgcn_exp2f((m - mn) * qscale);
;         lsum *= alpha;
; #pragma unroll
;         for (int i = 0; i < 16; ++i) { o[0][i] *= alpha; o[1][i] *= alpha; }
;       }
.LBB0_239:
	s_andn2_b64 vcc, exec, s[24:25]
	s_cbranch_vccnz .LBB0_245
	s_and_saveexec_b64 s[24:25], s[8:9]
	s_cbranch_execz .LBB0_244
	ds_read_b128 v[220:223], v155
	ds_read_b128 v[224:227], v155 offset:32
	ds_read_b128 v[228:231], v155 offset:64
	ds_read_b128 v[232:235], v155 offset:6688
	ds_read_b128 v[236:239], v155 offset:96
	ds_read_b128 v[240:243], v155 offset:128
	ds_read_b128 v[244:247], v155 offset:160
	ds_read_b128 v[248:251], v155 offset:6656
	s_waitcnt lgkmcnt(7)
	v_mfma_f32_32x32x16_bf16 v[50:65], v[220:223], v[66:69], 0
	ds_read_b128 v[220:223], v155 offset:6720
	s_waitcnt lgkmcnt(7)
	v_mfma_f32_32x32x16_bf16 v[50:65], v[224:227], v[70:73], v[50:65]
	ds_read_b128 v[224:227], v155 offset:6752
	s_waitcnt lgkmcnt(7)
	v_mfma_f32_32x32x16_bf16 v[50:65], v[228:231], v[74:77], v[50:65]
	ds_read_b128 v[228:231], v155 offset:6784
	s_waitcnt lgkmcnt(6)
	v_mfma_f32_32x32x16_bf16 v[50:65], v[236:239], v[78:81], v[50:65]
	ds_read_b128 v[236:239], v155 offset:6816
	s_waitcnt lgkmcnt(6)
	v_mfma_f32_32x32x16_bf16 v[50:65], v[240:243], v[82:85], v[50:65]
	s_waitcnt lgkmcnt(5)
	v_mfma_f32_32x32x16_bf16 v[50:65], v[244:247], v[86:89], v[50:65]
	s_waitcnt lgkmcnt(4)
	v_mfma_f32_32x32x16_bf16 v[34:49], v[248:251], v[66:69], 0
	s_nop 8
	s_nop 0
	v_max3_f32 v0, v50, s94, v51
	v_max3_f32 v0, v0, v52, v53
	v_max3_f32 v0, v0, v54, v55
	v_max3_f32 v0, v0, v56, v57
	v_max3_f32 v0, v0, v58, v59
	v_max3_f32 v0, v0, v60, v61
	v_max3_f32 v0, v0, v62, v63
	v_mfma_f32_32x32x16_bf16 v[34:49], v[232:235], v[70:73], v[34:49]
	v_max3_f32 v0, v0, v64, v65
	s_waitcnt lgkmcnt(3)
	v_mfma_f32_32x32x16_bf16 v[34:49], v[220:223], v[74:77], v[34:49]
	s_waitcnt lgkmcnt(2)
	v_mfma_f32_32x32x16_bf16 v[34:49], v[224:227], v[78:81], v[34:49]
	s_waitcnt lgkmcnt(1)
	v_mfma_f32_32x32x16_bf16 v[34:49], v[228:231], v[82:85], v[34:49]
	s_waitcnt lgkmcnt(0)
	v_mfma_f32_32x32x16_bf16 v[34:49], v[236:239], v[86:89], v[34:49]
	v_and_b32_e32 v159, 64, v172
	v_xor_b32_e32 v158, 32, v172
	v_add_u32_e32 v159, 64, v159
	v_cmp_lt_i32_e32 vcc, v158, v159
	s_nop 7
	v_max3_f32 v0, v0, v34, v35
	v_max3_f32 v0, v0, v36, v37
	v_max3_f32 v0, v0, v38, v39
	v_max3_f32 v0, v0, v40, v41
	v_max3_f32 v0, v0, v42, v43
	v_max3_f32 v0, v0, v44, v45
	v_max3_f32 v0, v0, v46, v47
	v_cndmask_b32_e32 v158, v172, v158, vcc
	v_max3_f32 v0, v0, v48, v49
	v_lshlrev_b32_e32 v158, 2, v158
	ds_bpermute_b32 v158, v158, v0
	s_waitcnt lgkmcnt(0)
	v_max3_f32 v0, v157, v0, v158
	v_cmp_neq_f32_e32 vcc, v0, v157
	s_cbranch_vccz .LBB0_243
	v_sub_f32_e32 v157, v157, v0
	v_mul_f32_e32 v157, 0x3e16c740, v157
	v_exp_f32_e32 v158, v157
	s_nop 0
	v_mul_f32_e32 v142, v142, v158
	v_pk_mul_f32 v[32:33], v[32:33], v[158:159] op_sel_hi:[1,0]
	v_pk_mul_f32 v[30:31], v[30:31], v[158:159] op_sel_hi:[1,0]
	v_pk_mul_f32 v[28:29], v[28:29], v[158:159] op_sel_hi:[1,0]
	v_pk_mul_f32 v[26:27], v[26:27], v[158:159] op_sel_hi:[1,0]
	v_pk_mul_f32 v[24:25], v[24:25], v[158:159] op_sel_hi:[1,0]
	v_pk_mul_f32 v[22:23], v[22:23], v[158:159] op_sel_hi:[1,0]
	v_pk_mul_f32 v[20:21], v[20:21], v[158:159] op_sel_hi:[1,0]
	v_pk_mul_f32 v[18:19], v[18:19], v[158:159] op_sel_hi:[1,0]
	v_pk_mul_f32 v[16:17], v[16:17], v[158:159] op_sel_hi:[1,0]
	v_pk_mul_f32 v[14:15], v[14:15], v[158:159] op_sel_hi:[1,0]
	v_pk_mul_f32 v[12:13], v[12:13], v[158:159] op_sel_hi:[1,0]
	v_pk_mul_f32 v[10:11], v[10:11], v[158:159] op_sel_hi:[1,0]
	v_pk_mul_f32 v[8:9], v[8:9], v[158:159] op_sel_hi:[1,0]
	v_pk_mul_f32 v[6:7], v[6:7], v[158:159] op_sel_hi:[1,0]
	v_pk_mul_f32 v[4:5], v[4:5], v[158:159] op_sel_hi:[1,0]
	v_pk_mul_f32 v[2:3], v[2:3], v[158:159] op_sel_hi:[1,0]
; DI unsigned pack2(float a, float b) { unsigned r; asm("v_cvt_pk_bf16_f32 %0, %1, %2\n\ts_nop 1" : "=v"(r) : "v"(a), "v"(b)); return r; }
; #define MFMA32(a, b, c) __builtin_amdgcn_mfma_f32_32x32x16_bf16((a), (b), (c), 0, 0, 0)
; template <int DQK, bool WIN>
; DI void attn_item(const u16* __restrict__ Qb, int ldq, const u16* __restrict__ Kb, int ldk, const u16* __restrict__ Vtb, int qb,
;                   float qscale, float sink2, const u16* __restrict__ zb, int ldz, u16* __restrict__ ob, int ldo, u16* lds) {
;     ...
;       m = mn;
;       const float nb = -mn * qscale;
;       float ps = 0.f;
; #pragma unroll
;       for (int kb = 0; kb < 2; ++kb)
; #pragma unroll
;         for (int i = 0; i < 16; ++i) { float pv = __builtin_amdgcn_exp2f(fmaf(st[kb][i], qscale, nb)); st[kb][i] = pv; ps += pv; }
;       lsum += ps;
; #pragma unroll
;       for (int kb = 0; kb < 2; ++kb)
; #pragma unroll
;         for (int s2 = 0; s2 < 2; ++s2) {
;           union { bf16x8 v; unsigned u[4]; } pf;
; #pragma unroll
;           for (int j = 0; j < 4; ++j) pf.u[j] = pack2(st[kb][8 * s2 + 2 * j], st[kb][8 * s2 + 2 * j + 1]);
; #pragma unroll
;           for (int vb = 0; vb < 2; ++vb) {
;             const bf16x8 vf = *(const bf16x8*)(vs + (vb * 32 + r) * 72 + (kb * 2 + s2) * 16 + hh * 8);
;             o[vb] = MFMA32(vf, pf.v, o[vb]);
;           }
;         }
.LBB0_243:
	ds_read_b128 v[220:223], v156 offset:13312
	ds_read_b128 v[224:227], v156 offset:13344
	ds_read_b128 v[228:231], v156 offset:17920
	ds_read_b128 v[232:235], v156 offset:17952
	ds_read_b128 v[236:239], v156 offset:13376
	ds_read_b128 v[240:243], v156 offset:17984
	ds_read_b128 v[244:247], v156 offset:13408
	ds_read_b128 v[248:251], v156 offset:18016
	v_mul_f32_e32 v157, 0xbe16c740, v0
	v_fmamk_f32 v50, v50, 0x3e16c740, v157
	v_exp_f32_e32 v50, v50
	v_fmamk_f32 v51, v51, 0x3e16c740, v157
	v_exp_f32_e32 v51, v51
	v_fmamk_f32 v52, v52, 0x3e16c740, v157
	v_exp_f32_e32 v52, v52
	v_fmamk_f32 v53, v53, 0x3e16c740, v157
	v_exp_f32_e32 v53, v53
	v_fmamk_f32 v54, v54, 0x3e16c740, v157
	v_add_f32_e32 v158, 0, v50
	v_exp_f32_e32 v54, v54
	v_fmamk_f32 v55, v55, 0x3e16c740, v157
	v_add_f32_e32 v158, v51, v158
	v_exp_f32_e32 v55, v55
	v_fmamk_f32 v56, v56, 0x3e16c740, v157
	v_add_f32_e32 v158, v52, v158
	v_exp_f32_e32 v56, v56
	v_fmamk_f32 v57, v57, 0x3e16c740, v157
	v_add_f32_e32 v158, v53, v158
	v_exp_f32_e32 v57, v57
	v_fmamk_f32 v58, v58, 0x3e16c740, v157
	v_add_f32_e32 v158, v54, v158
	v_exp_f32_e32 v58, v58
	v_fmamk_f32 v59, v59, 0x3e16c740, v157
	v_add_f32_e32 v158, v55, v158
	v_exp_f32_e32 v59, v59
	v_fmamk_f32 v60, v60, 0x3e16c740, v157
	v_add_f32_e32 v158, v56, v158
	v_exp_f32_e32 v60, v60
	v_fmamk_f32 v61, v61, 0x3e16c740, v157
	v_add_f32_e32 v158, v57, v158
	v_exp_f32_e32 v61, v61
	v_fmamk_f32 v62, v62, 0x3e16c740, v157
	v_add_f32_e32 v158, v58, v158
	v_exp_f32_e32 v62, v62
	v_fmamk_f32 v63, v63, 0x3e16c740, v157
	v_add_f32_e32 v158, v59, v158
	v_exp_f32_e32 v63, v63
	v_fmamk_f32 v64, v64, 0x3e16c740, v157
	v_add_f32_e32 v158, v60, v158
	v_exp_f32_e32 v64, v64
	v_fmamk_f32 v65, v65, 0x3e16c740, v157
	v_add_f32_e32 v158, v61, v158
	v_exp_f32_e32 v65, v65
	v_fmamk_f32 v34, v34, 0x3e16c740, v157
	v_add_f32_e32 v158, v62, v158
	v_exp_f32_e32 v159, v34
	v_add_f32_e32 v158, v63, v158
	v_add_f32_e32 v158, v64, v158
	v_add_f32_e32 v158, v65, v158
	v_fmamk_f32 v35, v35, 0x3e16c740, v157
	v_add_f32_e32 v34, v159, v158
	v_exp_f32_e32 v158, v35
	v_fmamk_f32 v35, v36, 0x3e16c740, v157
	v_exp_f32_e32 v160, v35
	v_fmamk_f32 v35, v37, 0x3e16c740, v157
	v_exp_f32_e32 v161, v35
	v_fmamk_f32 v35, v38, 0x3e16c740, v157
	v_exp_f32_e32 v162, v35
	v_fmamk_f32 v35, v39, 0x3e16c740, v157
	v_add_f32_e32 v34, v158, v34
	v_exp_f32_e32 v164, v35
	v_fmamk_f32 v35, v40, 0x3e16c740, v157
	v_add_f32_e32 v34, v160, v34
	v_exp_f32_e32 v165, v35
	v_fmamk_f32 v35, v41, 0x3e16c740, v157
	v_add_f32_e32 v34, v161, v34
	v_exp_f32_e32 v166, v35
	v_fmamk_f32 v35, v42, 0x3e16c740, v157
	v_add_f32_e32 v34, v162, v34
	v_exp_f32_e32 v167, v35
	v_fmamk_f32 v35, v43, 0x3e16c740, v157
	v_add_f32_e32 v34, v164, v34
	v_exp_f32_e32 v182, v35
	v_fmamk_f32 v35, v44, 0x3e16c740, v157
	v_add_f32_e32 v34, v165, v34
	v_exp_f32_e32 v183, v35
	v_fmamk_f32 v35, v45, 0x3e16c740, v157
	v_add_f32_e32 v34, v166, v34
	v_exp_f32_e32 v184, v35
	v_fmamk_f32 v35, v46, 0x3e16c740, v157
	v_add_f32_e32 v34, v167, v34
	v_exp_f32_e32 v46, v35
	v_fmamk_f32 v35, v47, 0x3e16c740, v157
	v_add_f32_e32 v34, v182, v34
	v_exp_f32_e32 v47, v35
	v_fmamk_f32 v35, v48, 0x3e16c740, v157
	v_add_f32_e32 v34, v183, v34
	v_exp_f32_e32 v48, v35
	v_fmac_f32_e32 v157, 0x3e16c740, v49
	v_add_f32_e32 v34, v184, v34
	v_exp_f32_e32 v49, v157
	v_add_f32_e32 v34, v46, v34
	v_add_f32_e32 v34, v47, v34
	v_add_f32_e32 v34, v48, v34
	v_add_f32_e32 v34, v49, v34
	v_add_f32_e32 v142, v34, v142
	v_cvt_pk_bf16_f32 v34, v50, v51
	s_nop 1
	v_cvt_pk_bf16_f32 v35, v52, v53
	s_nop 1
	v_cvt_pk_bf16_f32 v36, v54, v55
	s_nop 1
	v_cvt_pk_bf16_f32 v37, v56, v57
	s_nop 1
	v_mov_b32_e32 v157, v0
	s_waitcnt lgkmcnt(7)
	v_mfma_f32_32x32x16_bf16 v[18:33], v[220:223], v[34:37], v[18:33]
	s_waitcnt lgkmcnt(5)
	v_mfma_f32_32x32x16_bf16 v[2:17], v[228:231], v[34:37], v[2:17]
	v_cvt_pk_bf16_f32 v34, v58, v59
	s_nop 1
	v_cvt_pk_bf16_f32 v35, v60, v61
	s_nop 1
	v_cvt_pk_bf16_f32 v36, v62, v63
	s_nop 1
	v_cvt_pk_bf16_f32 v37, v64, v65
	s_nop 1
	s_waitcnt lgkmcnt(4)
	v_mfma_f32_32x32x16_bf16 v[2:17], v[232:235], v[34:37], v[2:17]
	v_mfma_f32_32x32x16_bf16 v[18:33], v[224:227], v[34:37], v[18:33]
	v_cvt_pk_bf16_f32 v34, v159, v158
	s_nop 1
	v_cvt_pk_bf16_f32 v35, v160, v161
	s_nop 1
	v_cvt_pk_bf16_f32 v36, v162, v164
	s_nop 1
	v_cvt_pk_bf16_f32 v37, v165, v166
	s_nop 1
	s_waitcnt lgkmcnt(3)
	v_mfma_f32_32x32x16_bf16 v[18:33], v[236:239], v[34:37], v[18:33]
	s_waitcnt lgkmcnt(2)
	v_mfma_f32_32x32x16_bf16 v[2:17], v[240:243], v[34:37], v[2:17]
	v_cvt_pk_bf16_f32 v34, v167, v182
	s_nop 1
	v_cvt_pk_bf16_f32 v35, v183, v184
	s_nop 1
	v_cvt_pk_bf16_f32 v36, v46, v47
	s_nop 1
	v_cvt_pk_bf16_f32 v37, v48, v49
	s_nop 1
	s_waitcnt lgkmcnt(1)
	v_mfma_f32_32x32x16_bf16 v[18:33], v[244:247], v[34:37], v[18:33]
	s_waitcnt lgkmcnt(0)
	v_mfma_f32_32x32x16_bf16 v[2:17], v[248:251], v[34:37], v[2:17]
.LBB0_244:
	s_or_b64 exec, exec, s[24:25]
	s_nop 7
	s_nop 0
	v_mov_b64_e32 v[48:49], v[32:33]
	s_nop 1
	v_mov_b64_e32 v[64:65], v[16:17]
	v_mov_b64_e32 v[46:47], v[30:31]
	v_mov_b64_e32 v[44:45], v[28:29]
	v_mov_b64_e32 v[42:43], v[26:27]
	v_mov_b64_e32 v[40:41], v[24:25]
	v_mov_b64_e32 v[38:39], v[22:23]
	v_mov_b64_e32 v[36:37], v[20:21]
	v_mov_b64_e32 v[34:35], v[18:19]
	v_mov_b64_e32 v[62:63], v[14:15]
	v_mov_b64_e32 v[60:61], v[12:13]
	v_mov_b64_e32 v[58:59], v[10:11]
	v_mov_b64_e32 v[56:57], v[8:9]
	v_mov_b64_e32 v[54:55], v[6:7]
	v_mov_b64_e32 v[52:53], v[4:5]
	v_mov_b64_e32 v[50:51], v[2:3]
	v_mov_b32_e32 v0, v142
	v_mov_b32_e32 v158, v157

; #define MFMA32(a, b, c) __builtin_amdgcn_mfma_f32_32x32x16_bf16((a), (b), (c), 0, 0, 0)
; template <int DQK, bool WIN>
; DI void attn_item(const u16* __restrict__ Qb, int ldq, const u16* __restrict__ Kb, int ldk, const u16* __restrict__ Vtb, int qb,
;                   float qscale, float sink2, const u16* __restrict__ zb, int ldz, u16* __restrict__ ob, int ldo, u16* lds) {
;     ...
;       for (int kb = 0; kb < 2; ++kb) {
; #pragma unroll
;         for (int i = 0; i < 16; ++i) st[kb][i] = 0.f;
; #pragma unroll
;         for (int s = 0; s < NKS; ++s) {
;           bf16x8 a = *(const bf16x8*)(ks + (kb * 32 + r) * KST + 16 * s + 8 * hh);
;           st[kb] = MFMA32(a, qf[s], st[kb]);
;         }
;       }
;       float mx = -INFINITY;
; #pragma unroll
;       for (int kb = 0; kb < 2; ++kb)
; #pragma unroll
;         for (int i = 0; i < 16; ++i) {
;           float v = st[kb][i];
;           if (MASK) {
;             int kg = k0 + kb * 32 + (i & 3) + 8 * (i >> 2) + 4 * hh;
;             bool ok = kg <= qrow;
;             if (WIN) ok = ok && (qrow - kg < 128);
;             v = ok ? v : -INFINITY;
;             st[kb][i] = v;
;           }
;           mx = fmaxf(mx, v);
;         }
;       mx = fmaxf(mx, __shfl_xor(mx, 32));
.LBB0_247:
	s_add_i32 s0, s20, 0xffffff80
	s_cmp_lt_u32 s31, s29
	v_cmp_le_i32_e64 s[8:9], s0, v154
	s_mov_b64 s[24:25], -1
	s_cbranch_scc1 .LBB0_257
	v_mov_b64_e32 v[2:3], v[50:51]
	v_mov_b64_e32 v[18:19], v[34:35]
	v_mov_b32_e32 v157, v158
	v_mov_b32_e32 v142, v0
	v_mov_b64_e32 v[4:5], v[52:53]
	v_mov_b64_e32 v[6:7], v[54:55]
	v_mov_b64_e32 v[8:9], v[56:57]
	v_mov_b64_e32 v[10:11], v[58:59]
	v_mov_b64_e32 v[12:13], v[60:61]
	v_mov_b64_e32 v[14:15], v[62:63]
	v_mov_b64_e32 v[16:17], v[64:65]
	v_mov_b64_e32 v[20:21], v[36:37]
	v_mov_b64_e32 v[22:23], v[38:39]
	v_mov_b64_e32 v[24:25], v[40:41]
	v_mov_b64_e32 v[26:27], v[42:43]
	v_mov_b64_e32 v[28:29], v[44:45]
	v_mov_b64_e32 v[30:31], v[46:47]
	v_mov_b64_e32 v[32:33], v[48:49]
	s_and_saveexec_b64 s[24:25], s[8:9]
	s_cbranch_execz .LBB0_252
	ds_read_b128 v[220:223], v155 offset:22528
	ds_read_b128 v[224:227], v155 offset:22560
	ds_read_b128 v[228:231], v155 offset:22592
	ds_read_b128 v[232:235], v155 offset:29216
	ds_read_b128 v[236:239], v155 offset:22624
	ds_read_b128 v[240:243], v155 offset:22656
	ds_read_b128 v[244:247], v155 offset:22688
	ds_read_b128 v[248:251], v155 offset:29184
	v_add_u32_e32 v142, s20, v146
	v_add_u32_e32 v157, 0xffffff80, v142
	v_cmp_le_i32_e32 vcc, v157, v130
	s_waitcnt lgkmcnt(7)
	v_mfma_f32_32x32x16_bf16 v[18:33], v[220:223], v[66:69], 0
	ds_read_b128 v[220:223], v155 offset:29248
	s_waitcnt lgkmcnt(7)
	v_mfma_f32_32x32x16_bf16 v[18:33], v[224:227], v[70:73], v[18:33]
	ds_read_b128 v[224:227], v155 offset:29280
	s_waitcnt lgkmcnt(7)
	v_mfma_f32_32x32x16_bf16 v[18:33], v[228:231], v[74:77], v[18:33]
	ds_read_b128 v[228:231], v155 offset:29312
	s_waitcnt lgkmcnt(6)
	v_mfma_f32_32x32x16_bf16 v[18:33], v[236:239], v[78:81], v[18:33]
	ds_read_b128 v[236:239], v155 offset:29344
	s_waitcnt lgkmcnt(6)
	v_mfma_f32_32x32x16_bf16 v[18:33], v[240:243], v[82:85], v[18:33]
	s_waitcnt lgkmcnt(5)
	v_mfma_f32_32x32x16_bf16 v[18:33], v[244:247], v[86:89], v[18:33]
	s_waitcnt lgkmcnt(4)
	v_mfma_f32_32x32x16_bf16 v[2:17], v[248:251], v[66:69], 0
	v_mfma_f32_32x32x16_bf16 v[2:17], v[232:235], v[70:73], v[2:17]
	s_waitcnt lgkmcnt(3)
	v_mfma_f32_32x32x16_bf16 v[2:17], v[220:223], v[74:77], v[2:17]
	s_waitcnt lgkmcnt(2)
	v_mfma_f32_32x32x16_bf16 v[2:17], v[224:227], v[78:81], v[2:17]
	s_waitcnt lgkmcnt(1)
	v_mfma_f32_32x32x16_bf16 v[2:17], v[228:231], v[82:85], v[2:17]
	s_waitcnt lgkmcnt(0)
	v_mfma_f32_32x32x16_bf16 v[2:17], v[236:239], v[86:89], v[2:17]
	s_nop 0
	v_cndmask_b32_e32 v167, v176, v18, vcc
	v_cmp_lt_i32_e32 vcc, v157, v130
	s_nop 1
	v_cndmask_b32_e32 v166, v176, v19, vcc
	v_add_u32_e32 v19, 0xffffff82, v142
	v_cmp_le_i32_e32 vcc, v19, v130
	v_add_u32_e32 v19, 0xffffff83, v142
	v_max3_f32 v18, v167, s94, v166
	v_cndmask_b32_e32 v182, v176, v20, vcc
	v_cmp_le_i32_e32 vcc, v19, v130
	v_add_u32_e32 v19, 0xffffff88, v142
	s_nop 0
	v_cndmask_b32_e32 v183, v176, v21, vcc
	v_cmp_le_i32_e32 vcc, v19, v130
	v_add_u32_e32 v19, 0xffffff89, v142
	v_max3_f32 v18, v18, v182, v183
	v_cndmask_b32_e32 v185, v176, v22, vcc
	v_cmp_le_i32_e32 vcc, v19, v130
	v_add_u32_e32 v19, 0xffffff8a, v142
	s_nop 0
	v_cndmask_b32_e32 v186, v176, v23, vcc
	v_cmp_le_i32_e32 vcc, v19, v130
	v_add_u32_e32 v19, 0xffffff8b, v142
	v_max3_f32 v18, v18, v185, v186
	v_cndmask_b32_e32 v190, v176, v24, vcc
	v_cmp_le_i32_e32 vcc, v19, v130
	v_add_u32_e32 v19, 0xffffff90, v142
	s_nop 0
	v_cndmask_b32_e32 v191, v176, v25, vcc
	v_cmp_le_i32_e32 vcc, v19, v130
	v_add_u32_e32 v19, 0xffffff91, v142
	v_max3_f32 v18, v18, v190, v191
	v_cndmask_b32_e32 v201, v176, v26, vcc
	v_cmp_le_i32_e32 vcc, v19, v130
	v_add_u32_e32 v19, 0xffffff92, v142
	s_nop 0
	v_cndmask_b32_e32 v195, v176, v27, vcc
	v_cmp_le_i32_e32 vcc, v19, v130
	v_add_u32_e32 v19, 0xffffff93, v142
	v_max3_f32 v18, v18, v201, v195
	v_cndmask_b32_e32 v202, v176, v28, vcc
	v_cmp_le_i32_e32 vcc, v19, v130
	v_add_u32_e32 v19, 0xffffff98, v142
	s_nop 0
	v_cndmask_b32_e32 v196, v176, v29, vcc
	v_cmp_le_i32_e32 vcc, v19, v130
	v_add_u32_e32 v19, 0xffffff99, v142
	v_max3_f32 v18, v18, v202, v196
	v_cndmask_b32_e32 v203, v176, v30, vcc
	v_cmp_le_i32_e32 vcc, v19, v130
	v_add_u32_e32 v19, 0xffffff9a, v142
	s_nop 0
	v_cndmask_b32_e32 v197, v176, v31, vcc
	v_cmp_le_i32_e32 vcc, v19, v130
	v_add_u32_e32 v19, 0xffffff9b, v142
	v_max3_f32 v18, v18, v203, v197
	v_cndmask_b32_e32 v204, v176, v32, vcc
	v_cmp_le_i32_e32 vcc, v19, v130
	v_add_u32_e32 v19, 0xffffffa0, v142
	s_nop 0
	v_cndmask_b32_e32 v198, v176, v33, vcc
	v_cmp_le_i32_e32 vcc, v19, v130
	v_max3_f32 v18, v18, v204, v198
	s_nop 0
	v_cndmask_b32_e32 v205, v176, v2, vcc
	v_add_u32_e32 v2, 0xffffffa1, v142
	v_cmp_le_i32_e32 vcc, v2, v130
	s_nop 1
	v_cndmask_b32_e32 v199, v176, v3, vcc
	v_add_u32_e32 v3, 0xffffffa2, v142
	v_cmp_le_i32_e32 vcc, v3, v130
	v_add_u32_e32 v3, 0xffffffa3, v142
	v_max3_f32 v2, v18, v205, v199
	v_cndmask_b32_e32 v200, v176, v4, vcc
	v_cmp_le_i32_e32 vcc, v3, v130
	v_add_u32_e32 v3, 0xffffffa8, v142
	v_and_b32_e32 v4, 64, v172
	v_cndmask_b32_e32 v193, v176, v5, vcc
	v_cmp_le_i32_e32 vcc, v3, v130
	v_add_u32_e32 v3, 0xffffffa9, v142
	v_max3_f32 v2, v2, v200, v193
	v_cndmask_b32_e32 v194, v176, v6, vcc
	v_cmp_le_i32_e32 vcc, v3, v130
	v_add_u32_e32 v3, 0xffffffaa, v142
	v_add_u32_e32 v4, 64, v4
	v_cndmask_b32_e32 v192, v176, v7, vcc
	v_cmp_le_i32_e32 vcc, v3, v130
	v_add_u32_e32 v3, 0xffffffab, v142
	v_max3_f32 v2, v2, v194, v192
	v_cndmask_b32_e32 v187, v176, v8, vcc
	v_cmp_le_i32_e32 vcc, v3, v130
	v_add_u32_e32 v3, 0xffffffb0, v142
	v_mov_b64_e32 v[18:19], v[34:35]
	v_cndmask_b32_e32 v188, v176, v9, vcc
	v_cmp_le_i32_e32 vcc, v3, v130
	v_add_u32_e32 v3, 0xffffffb1, v142
	v_max3_f32 v2, v2, v187, v188
	v_cndmask_b32_e32 v189, v176, v10, vcc
	v_cmp_le_i32_e32 vcc, v3, v130
	v_add_u32_e32 v3, 0xffffffb2, v142
	v_mov_b64_e32 v[20:21], v[36:37]
	v_cndmask_b32_e32 v184, v176, v11, vcc
	v_cmp_le_i32_e32 vcc, v3, v130
	v_add_u32_e32 v3, 0xffffffb3, v142
	v_max3_f32 v2, v2, v189, v184
	v_cndmask_b32_e32 v165, v176, v12, vcc
	v_cmp_le_i32_e32 vcc, v3, v130
	v_add_u32_e32 v3, 0xffffffb8, v142
	v_mov_b64_e32 v[22:23], v[38:39]
	v_cndmask_b32_e32 v164, v176, v13, vcc
	v_cmp_le_i32_e32 vcc, v3, v130
	v_add_u32_e32 v3, 0xffffffb9, v142
	v_max3_f32 v2, v2, v165, v164
	v_cndmask_b32_e32 v160, v176, v14, vcc
	v_cmp_le_i32_e32 vcc, v3, v130
	v_add_u32_e32 v3, 0xffffffba, v142
	v_mov_b64_e32 v[24:25], v[40:41]
	v_cndmask_b32_e32 v161, v176, v15, vcc
	v_cmp_le_i32_e32 vcc, v3, v130
	v_add_u32_e32 v3, 0xffffffbb, v142
	v_max3_f32 v2, v2, v160, v161
	v_cndmask_b32_e32 v162, v176, v16, vcc
	v_cmp_le_i32_e32 vcc, v3, v130
	v_xor_b32_e32 v3, 32, v172
	v_mov_b64_e32 v[26:27], v[42:43]
	v_cndmask_b32_e32 v159, v176, v17, vcc
	v_cmp_lt_i32_e32 vcc, v3, v4
	v_max3_f32 v2, v2, v162, v159
	v_mov_b64_e32 v[28:29], v[44:45]
	v_cndmask_b32_e32 v3, v172, v3, vcc
	v_lshlrev_b32_e32 v3, 2, v3
	ds_bpermute_b32 v3, v3, v2
	v_mov_b64_e32 v[30:31], v[46:47]
	v_mov_b64_e32 v[32:33], v[48:49]
	v_mov_b32_e32 v142, v0
	s_waitcnt lgkmcnt(0)
; DI unsigned pack2(float a, float b) { unsigned r; asm("v_cvt_pk_bf16_f32 %0, %1, %2\n\ts_nop 1" : "=v"(r) : "v"(a), "v"(b)); return r; }
; #define MFMA32(a, b, c) __builtin_amdgcn_mfma_f32_32x32x16_bf16((a), (b), (c), 0, 0, 0)
; template <int DQK, bool WIN>
; DI void attn_item(const u16* __restrict__ Qb, int ldq, const u16* __restrict__ Kb, int ldk, const u16* __restrict__ Vtb, int qb,
;                   float qscale, float sink2, const u16* __restrict__ zb, int ldz, u16* __restrict__ ob, int ldo, u16* lds) {
;     ...
;       const float mn = fmaxf(m, mx);
;       if (__any(mn != m)) {
;         const float alpha = __builtin_amdgcn_exp2f((m - mn) * qscale);
;         lsum *= alpha;
; #pragma unroll
;         for (int i = 0; i < 16; ++i) { o[0][i] *= alpha; o[1][i] *= alpha; }
;       }
;       m = mn;
;       const float nb = -mn * qscale;
;       float ps = 0.f;
; #pragma unroll
;       for (int kb = 0; kb < 2; ++kb)
; #pragma unroll
;         for (int i = 0; i < 16; ++i) { float pv = __builtin_amdgcn_exp2f(fmaf(st[kb][i], qscale, nb)); st[kb][i] = pv; ps += pv; }
;       lsum += ps;
; #pragma unroll
;       for (int kb = 0; kb < 2; ++kb)
; #pragma unroll
;         for (int s2 = 0; s2 < 2; ++s2) {
;           union { bf16x8 v; unsigned u[4]; } pf;
; #pragma unroll
;           for (int j = 0; j < 4; ++j) pf.u[j] = pack2(st[kb][8 * s2 + 2 * j], st[kb][8 * s2 + 2 * j + 1]);
; #pragma unroll
;           for (int vb = 0; vb < 2; ++vb) {
;             const bf16x8 vf = *(const bf16x8*)(vs + (vb * 32 + r) * 72 + (kb * 2 + s2) * 16 + hh * 8);
;             o[vb] = MFMA32(vf, pf.v, o[vb]);
;           }
;         }
	v_max3_f32 v157, v158, v2, v3
	v_mov_b64_e32 v[2:3], v[50:51]
	v_cmp_neq_f32_e32 vcc, v157, v158
	v_mov_b64_e32 v[4:5], v[52:53]
	v_mov_b64_e32 v[6:7], v[54:55]
	v_mov_b64_e32 v[8:9], v[56:57]
	v_mov_b64_e32 v[10:11], v[58:59]
	v_mov_b64_e32 v[12:13], v[60:61]
	v_mov_b64_e32 v[14:15], v[62:63]
	v_mov_b64_e32 v[16:17], v[64:65]
	s_cbranch_vccz .LBB0_251
	v_sub_f32_e32 v2, v158, v157
	v_mul_f32_e32 v2, 0x3e16c740, v2
	v_exp_f32_e32 v2, v2
	s_nop 0
	v_mul_f32_e32 v142, v0, v2
	v_pk_mul_f32 v[32:33], v[48:49], v[2:3] op_sel_hi:[1,0]
	v_pk_mul_f32 v[30:31], v[46:47], v[2:3] op_sel_hi:[1,0]
	v_pk_mul_f32 v[28:29], v[44:45], v[2:3] op_sel_hi:[1,0]
	v_pk_mul_f32 v[26:27], v[42:43], v[2:3] op_sel_hi:[1,0]
	v_pk_mul_f32 v[24:25], v[40:41], v[2:3] op_sel_hi:[1,0]
	v_pk_mul_f32 v[22:23], v[38:39], v[2:3] op_sel_hi:[1,0]
	v_pk_mul_f32 v[20:21], v[36:37], v[2:3] op_sel_hi:[1,0]
	v_pk_mul_f32 v[18:19], v[34:35], v[2:3] op_sel_hi:[1,0]
	v_pk_mul_f32 v[16:17], v[64:65], v[2:3] op_sel_hi:[1,0]
	v_pk_mul_f32 v[14:15], v[62:63], v[2:3] op_sel_hi:[1,0]
	v_pk_mul_f32 v[12:13], v[60:61], v[2:3] op_sel_hi:[1,0]
	v_pk_mul_f32 v[10:11], v[58:59], v[2:3] op_sel_hi:[1,0]
	v_pk_mul_f32 v[8:9], v[56:57], v[2:3] op_sel_hi:[1,0]
	v_pk_mul_f32 v[6:7], v[54:55], v[2:3] op_sel_hi:[1,0]
	v_pk_mul_f32 v[4:5], v[52:53], v[2:3] op_sel_hi:[1,0]
	v_pk_mul_f32 v[2:3], v[50:51], v[2:3] op_sel_hi:[1,0]
.LBB0_251:
	ds_read_b128 v[220:223], v156 offset:35840
	ds_read_b128 v[224:227], v156 offset:35872
	ds_read_b128 v[228:231], v156 offset:40480
	ds_read_b128 v[232:235], v156 offset:35904
	ds_read_b128 v[236:239], v156 offset:40512
	ds_read_b128 v[240:243], v156 offset:35936
	v_mul_f32_e32 v206, 0xbe16c740, v157
	v_fmamk_f32 v167, v167, 0x3e16c740, v206
	v_exp_f32_e32 v167, v167
	v_fmamk_f32 v166, v166, 0x3e16c740, v206
	v_exp_f32_e32 v166, v166
	v_fmamk_f32 v182, v182, 0x3e16c740, v206
	v_exp_f32_e32 v182, v182
	v_fmamk_f32 v183, v183, 0x3e16c740, v206
	v_exp_f32_e32 v183, v183
	v_fmamk_f32 v185, v185, 0x3e16c740, v206
	v_add_f32_e32 v207, 0, v167
	v_exp_f32_e32 v185, v185
	v_fmamk_f32 v186, v186, 0x3e16c740, v206
	v_add_f32_e32 v207, v166, v207
	v_exp_f32_e32 v186, v186
	v_fmamk_f32 v190, v190, 0x3e16c740, v206
	v_add_f32_e32 v207, v182, v207
	v_exp_f32_e32 v208, v190
	v_fmamk_f32 v191, v191, 0x3e16c740, v206
	v_add_f32_e32 v190, v183, v207
	v_exp_f32_e32 v207, v191
	v_fmamk_f32 v191, v201, 0x3e16c740, v206
	v_add_f32_e32 v190, v185, v190
	v_exp_f32_e32 v209, v191
	v_fmamk_f32 v191, v195, 0x3e16c740, v206
	v_add_f32_e32 v190, v186, v190
	v_exp_f32_e32 v210, v191
	v_fmamk_f32 v191, v202, 0x3e16c740, v206
	v_add_f32_e32 v190, v208, v190
	v_exp_f32_e32 v202, v191
	v_fmamk_f32 v191, v196, 0x3e16c740, v206
	v_add_f32_e32 v190, v207, v190
	v_exp_f32_e32 v211, v191
	v_fmamk_f32 v191, v203, 0x3e16c740, v206
	v_add_f32_e32 v190, v209, v190
	v_exp_f32_e32 v203, v191
	v_fmamk_f32 v191, v197, 0x3e16c740, v206
	v_add_f32_e32 v190, v210, v190
	v_exp_f32_e32 v212, v191
	v_fmamk_f32 v191, v204, 0x3e16c740, v206
	v_add_f32_e32 v190, v202, v190
	v_exp_f32_e32 v204, v191
	v_fmamk_f32 v191, v198, 0x3e16c740, v206
	v_add_f32_e32 v190, v211, v190
	v_exp_f32_e32 v213, v191
	v_fmamk_f32 v191, v205, 0x3e16c740, v206
	v_add_f32_e32 v190, v203, v190
	v_exp_f32_e32 v205, v191
	v_fmamk_f32 v191, v199, 0x3e16c740, v206
	v_add_f32_e32 v190, v212, v190
	v_exp_f32_e32 v214, v191
	v_fmamk_f32 v191, v200, 0x3e16c740, v206
	v_add_f32_e32 v190, v204, v190
	v_exp_f32_e32 v215, v191
	v_add_f32_e32 v190, v213, v190
	v_add_f32_e32 v190, v205, v190
	v_add_f32_e32 v190, v214, v190
	v_add_f32_e32 v195, v215, v190
	v_fmamk_f32 v190, v193, 0x3e16c740, v206
	v_exp_f32_e32 v216, v190
	v_fmamk_f32 v190, v194, 0x3e16c740, v206
	v_exp_f32_e32 v217, v190
	v_fmamk_f32 v190, v192, 0x3e16c740, v206
	v_exp_f32_e32 v218, v190
	v_add_f32_e32 v194, v216, v195
	v_add_f32_e32 v194, v217, v194
	v_add_f32_e32 v219, v218, v194
	v_cvt_pk_bf16_f32 v194, v167, v166
	s_nop 1
	v_fmamk_f32 v166, v187, 0x3e16c740, v206
	v_exp_f32_e32 v167, v166
	v_fmamk_f32 v166, v188, 0x3e16c740, v206
	v_cvt_pk_bf16_f32 v196, v185, v186
	s_nop 1
	v_cvt_pk_bf16_f32 v197, v208, v207
	s_nop 1
	ds_read_b128 v[198:201], v156 offset:40448
	v_exp_f32_e32 v207, v166
	v_fmamk_f32 v166, v189, 0x3e16c740, v206
	v_cvt_pk_bf16_f32 v195, v182, v183
	s_nop 1
	v_exp_f32_e32 v208, v166
	s_waitcnt lgkmcnt(6)
	v_mfma_f32_32x32x16_bf16 v[18:33], v[220:223], v[194:197], v[18:33]
	v_fmamk_f32 v166, v184, 0x3e16c740, v206
	v_cvt_pk_bf16_f32 v182, v209, v210
	s_nop 1
	v_cvt_pk_bf16_f32 v183, v202, v211
	s_nop 1
	v_cvt_pk_bf16_f32 v184, v203, v212
	s_nop 1
	v_cvt_pk_bf16_f32 v185, v204, v213
	s_nop 1
	v_fmamk_f32 v165, v165, 0x3e16c740, v206
	s_waitcnt lgkmcnt(0)
	v_mfma_f32_32x32x16_bf16 v[18:33], v[224:227], v[182:185], v[18:33]
	v_fmamk_f32 v164, v164, 0x3e16c740, v206
	v_fmamk_f32 v160, v160, 0x3e16c740, v206
	v_exp_f32_e32 v160, v160
	v_fmamk_f32 v161, v161, 0x3e16c740, v206
	v_fmamk_f32 v162, v162, 0x3e16c740, v206
	v_fmac_f32_e32 v206, 0x3e16c740, v159
	v_mfma_f32_32x32x16_bf16 v[2:17], v[198:201], v[194:197], v[2:17]
	v_exp_f32_e32 v194, v166
	v_add_f32_e32 v166, v167, v219
	v_add_f32_e32 v166, v207, v166
	v_add_f32_e32 v166, v208, v166
	v_add_f32_e32 v195, v194, v166
	v_exp_f32_e32 v196, v165
	v_cvt_pk_bf16_f32 v165, v215, v216
	s_nop 1
	s_waitcnt lgkmcnt(0)
	v_mfma_f32_32x32x16_bf16 v[2:17], v[228:231], v[182:185], v[2:17]
	v_exp_f32_e32 v190, v164
	v_cvt_pk_bf16_f32 v164, v205, v214
	s_nop 1
	v_cvt_pk_bf16_f32 v166, v217, v218
	s_nop 1
	v_cvt_pk_bf16_f32 v167, v167, v207
	s_nop 1
	v_exp_f32_e32 v161, v161
	v_exp_f32_e32 v162, v162
	s_waitcnt lgkmcnt(0)
	v_mfma_f32_32x32x16_bf16 v[18:33], v[232:235], v[164:167], v[18:33]
	v_exp_f32_e32 v159, v206
	s_waitcnt lgkmcnt(0)
	v_mfma_f32_32x32x16_bf16 v[2:17], v[236:239], v[164:167], v[2:17]
	ds_read_b128 v[182:185], v156 offset:40544
	v_cvt_pk_bf16_f32 v164, v208, v194
	s_nop 1
	v_cvt_pk_bf16_f32 v165, v196, v190
	s_nop 1
	v_cvt_pk_bf16_f32 v166, v160, v161
	s_nop 1
	v_cvt_pk_bf16_f32 v167, v162, v159
	s_nop 1
	s_waitcnt lgkmcnt(1)
	v_mfma_f32_32x32x16_bf16 v[18:33], v[240:243], v[164:167], v[18:33]
	v_add_f32_e32 v186, v196, v195
	v_add_f32_e32 v186, v190, v186
	v_add_f32_e32 v160, v160, v186
	v_add_f32_e32 v160, v161, v160
	v_add_f32_e32 v160, v162, v160
	v_add_f32_e32 v159, v159, v160
	v_add_f32_e32 v142, v159, v142
	s_waitcnt lgkmcnt(0)
	v_mfma_f32_32x32x16_bf16 v[2:17], v[182:185], v[164:167], v[2:17]

; #define MFMA32(a, b, c) __builtin_amdgcn_mfma_f32_32x32x16_bf16((a), (b), (c), 0, 0, 0)
; template <int DQK, bool WIN>
; DI void attn_item(const u16* __restrict__ Qb, int ldq, const u16* __restrict__ Kb, int ldk, const u16* __restrict__ Vtb, int qb,
;                   float qscale, float sink2, const u16* __restrict__ zb, int ldz, u16* __restrict__ ob, int ldo, u16* lds) {
;     ...
;       for (int kb = 0; kb < 2; ++kb) {
; #pragma unroll
;         for (int i = 0; i < 16; ++i) st[kb][i] = 0.f;
; #pragma unroll
;         for (int s = 0; s < NKS; ++s) {
;           bf16x8 a = *(const bf16x8*)(ks + (kb * 32 + r) * KST + 16 * s + 8 * hh);
;           st[kb] = MFMA32(a, qf[s], st[kb]);
;         }
;       }
;       float mx = -INFINITY;
; #pragma unroll
;       for (int kb = 0; kb < 2; ++kb)
; #pragma unroll
;         for (int i = 0; i < 16; ++i) {
;           float v = st[kb][i];
;           if (MASK) {
;             int kg = k0 + kb * 32 + (i & 3) + 8 * (i >> 2) + 4 * hh;
;             bool ok = kg <= qrow;
;             if (WIN) ok = ok && (qrow - kg < 128);
;             v = ok ? v : -INFINITY;
;             st[kb][i] = v;
;           }
;           mx = fmaxf(mx, v);
;         }
;       mx = fmaxf(mx, __shfl_xor(mx, 32));
;       const float mn = fmaxf(m, mx);
;       if (__any(mn != m)) {
;         const float alpha = __builtin_amdgcn_exp2f((m - mn) * qscale);
;         lsum *= alpha;
; #pragma unroll
;         for (int i = 0; i < 16; ++i) { o[0][i] *= alpha; o[1][i] *= alpha; }
;       }
.LBB0_258:
	s_and_saveexec_b64 s[24:25], s[8:9]
	s_cbranch_execz .LBB0_262
	ds_read_b128 v[220:223], v155 offset:22528
	ds_read_b128 v[224:227], v155 offset:22560
	ds_read_b128 v[228:231], v155 offset:22592
	ds_read_b128 v[232:235], v155 offset:29216
	ds_read_b128 v[236:239], v155 offset:22624
	ds_read_b128 v[240:243], v155 offset:22656
	ds_read_b128 v[244:247], v155 offset:22688
	ds_read_b128 v[248:251], v155 offset:29184
	s_nop 7
	v_and_b32_e32 v159, 64, v172
	v_xor_b32_e32 v157, 32, v172
	v_add_u32_e32 v159, 64, v159
	s_waitcnt lgkmcnt(7)
	v_mfma_f32_32x32x16_bf16 v[18:33], v[220:223], v[66:69], 0
	ds_read_b128 v[220:223], v155 offset:29248
	v_cmp_lt_i32_e32 vcc, v157, v159
	s_nop 1
	v_cndmask_b32_e32 v157, v172, v157, vcc
	v_lshlrev_b32_e32 v157, 2, v157
	s_waitcnt lgkmcnt(7)
	v_mfma_f32_32x32x16_bf16 v[18:33], v[224:227], v[70:73], v[18:33]
	ds_read_b128 v[224:227], v155 offset:29280
	s_waitcnt lgkmcnt(7)
	v_mfma_f32_32x32x16_bf16 v[18:33], v[228:231], v[74:77], v[18:33]
	ds_read_b128 v[228:231], v155 offset:29312
	s_waitcnt lgkmcnt(6)
	v_mfma_f32_32x32x16_bf16 v[18:33], v[236:239], v[78:81], v[18:33]
	s_waitcnt lgkmcnt(5)
	v_mfma_f32_32x32x16_bf16 v[18:33], v[240:243], v[82:85], v[18:33]
	s_waitcnt lgkmcnt(4)
	v_mfma_f32_32x32x16_bf16 v[18:33], v[244:247], v[86:89], v[18:33]
	s_waitcnt lgkmcnt(3)
	v_mfma_f32_32x32x16_bf16 v[2:17], v[248:251], v[66:69], 0
	s_nop 8
	s_nop 0
	v_max3_f32 v142, v18, s94, v19
	v_max3_f32 v142, v142, v20, v21
	v_max3_f32 v142, v142, v22, v23
	v_max3_f32 v142, v142, v24, v25
	v_max3_f32 v142, v142, v26, v27
	v_max3_f32 v142, v142, v28, v29
	v_max3_f32 v142, v142, v30, v31
	v_mfma_f32_32x32x16_bf16 v[2:17], v[232:235], v[70:73], v[2:17]
	v_max3_f32 v142, v142, v32, v33
	s_waitcnt lgkmcnt(2)
	v_mfma_f32_32x32x16_bf16 v[2:17], v[220:223], v[74:77], v[2:17]
	s_waitcnt lgkmcnt(1)
	v_mfma_f32_32x32x16_bf16 v[2:17], v[224:227], v[78:81], v[2:17]
	s_waitcnt lgkmcnt(0)
	v_mfma_f32_32x32x16_bf16 v[2:17], v[228:231], v[82:85], v[2:17]
	ds_read_b128 v[164:167], v155 offset:29344
	s_waitcnt lgkmcnt(0)
	v_mfma_f32_32x32x16_bf16 v[2:17], v[164:167], v[86:89], v[2:17]
	s_nop 11
	v_max3_f32 v142, v142, v2, v3
	v_max3_f32 v142, v142, v4, v5
	v_max3_f32 v142, v142, v6, v7
	v_max3_f32 v142, v142, v8, v9
	v_max3_f32 v142, v142, v10, v11
	v_max3_f32 v142, v142, v12, v13
	v_max3_f32 v142, v142, v14, v15
	v_max3_f32 v142, v142, v16, v17
	ds_bpermute_b32 v157, v157, v142
	s_waitcnt lgkmcnt(0)
	v_max3_f32 v142, v158, v142, v157
	v_cmp_neq_f32_e32 vcc, v142, v158
	s_cbranch_vccz .LBB0_261
	v_sub_f32_e32 v157, v158, v142
	v_mul_f32_e32 v157, 0x3e16c740, v157
	v_exp_f32_e32 v158, v157
	s_nop 0
	v_mul_f32_e32 v0, v0, v158
	v_pk_mul_f32 v[48:49], v[48:49], v[158:159] op_sel_hi:[1,0]
	v_pk_mul_f32 v[46:47], v[46:47], v[158:159] op_sel_hi:[1,0]
	v_pk_mul_f32 v[44:45], v[44:45], v[158:159] op_sel_hi:[1,0]
	v_pk_mul_f32 v[42:43], v[42:43], v[158:159] op_sel_hi:[1,0]
	v_pk_mul_f32 v[40:41], v[40:41], v[158:159] op_sel_hi:[1,0]
	v_pk_mul_f32 v[38:39], v[38:39], v[158:159] op_sel_hi:[1,0]
	v_pk_mul_f32 v[36:37], v[36:37], v[158:159] op_sel_hi:[1,0]
	v_pk_mul_f32 v[34:35], v[34:35], v[158:159] op_sel_hi:[1,0]
	v_pk_mul_f32 v[64:65], v[64:65], v[158:159] op_sel_hi:[1,0]
	v_pk_mul_f32 v[62:63], v[62:63], v[158:159] op_sel_hi:[1,0]
	v_pk_mul_f32 v[60:61], v[60:61], v[158:159] op_sel_hi:[1,0]
	v_pk_mul_f32 v[58:59], v[58:59], v[158:159] op_sel_hi:[1,0]
	v_pk_mul_f32 v[56:57], v[56:57], v[158:159] op_sel_hi:[1,0]
	v_pk_mul_f32 v[54:55], v[54:55], v[158:159] op_sel_hi:[1,0]
	v_pk_mul_f32 v[52:53], v[52:53], v[158:159] op_sel_hi:[1,0]
	v_pk_mul_f32 v[50:51], v[50:51], v[158:159] op_sel_hi:[1,0]
; DI unsigned pack2(float a, float b) { unsigned r; asm("v_cvt_pk_bf16_f32 %0, %1, %2\n\ts_nop 1" : "=v"(r) : "v"(a), "v"(b)); return r; }
; #define MFMA32(a, b, c) __builtin_amdgcn_mfma_f32_32x32x16_bf16((a), (b), (c), 0, 0, 0)
; template <int DQK, bool WIN>
; DI void attn_item(const u16* __restrict__ Qb, int ldq, const u16* __restrict__ Kb, int ldk, const u16* __restrict__ Vtb, int qb,
;                   float qscale, float sink2, const u16* __restrict__ zb, int ldz, u16* __restrict__ ob, int ldo, u16* lds) {
;     ...
;       m = mn;
;       const float nb = -mn * qscale;
;       float ps = 0.f;
; #pragma unroll
;       for (int kb = 0; kb < 2; ++kb)
; #pragma unroll
;         for (int i = 0; i < 16; ++i) { float pv = __builtin_amdgcn_exp2f(fmaf(st[kb][i], qscale, nb)); st[kb][i] = pv; ps += pv; }
;       lsum += ps;
; #pragma unroll
;       for (int kb = 0; kb < 2; ++kb)
; #pragma unroll
;         for (int s2 = 0; s2 < 2; ++s2) {
;           union { bf16x8 v; unsigned u[4]; } pf;
; #pragma unroll
;           for (int j = 0; j < 4; ++j) pf.u[j] = pack2(st[kb][8 * s2 + 2 * j], st[kb][8 * s2 + 2 * j + 1]);
; #pragma unroll
;           for (int vb = 0; vb < 2; ++vb) {
;             const bf16x8 vf = *(const bf16x8*)(vs + (vb * 32 + r) * 72 + (kb * 2 + s2) * 16 + hh * 8);
;             o[vb] = MFMA32(vf, pf.v, o[vb]);
;           }
;         }
.LBB0_261:
	ds_read_b128 v[220:223], v156 offset:35840
	ds_read_b128 v[224:227], v156 offset:35872
	ds_read_b128 v[228:231], v156 offset:40448
	ds_read_b128 v[232:235], v156 offset:40480
	ds_read_b128 v[236:239], v156 offset:35904
	ds_read_b128 v[240:243], v156 offset:40512
	ds_read_b128 v[244:247], v156 offset:35936
	ds_read_b128 v[248:251], v156 offset:40544
	v_mul_f32_e32 v157, 0xbe16c740, v142
	v_fmamk_f32 v18, v18, 0x3e16c740, v157
	v_exp_f32_e32 v18, v18
	v_fmamk_f32 v19, v19, 0x3e16c740, v157
	v_exp_f32_e32 v19, v19
	v_fmamk_f32 v20, v20, 0x3e16c740, v157
	v_exp_f32_e32 v20, v20
	v_fmamk_f32 v21, v21, 0x3e16c740, v157
	v_exp_f32_e32 v21, v21
	v_fmamk_f32 v22, v22, 0x3e16c740, v157
	v_add_f32_e32 v158, 0, v18
	v_exp_f32_e32 v22, v22
	v_fmamk_f32 v23, v23, 0x3e16c740, v157
	v_add_f32_e32 v158, v19, v158
	v_exp_f32_e32 v23, v23
	v_fmamk_f32 v24, v24, 0x3e16c740, v157
	v_add_f32_e32 v158, v20, v158
	v_exp_f32_e32 v24, v24
	v_fmamk_f32 v25, v25, 0x3e16c740, v157
	v_add_f32_e32 v158, v21, v158
	v_exp_f32_e32 v25, v25
	v_fmamk_f32 v26, v26, 0x3e16c740, v157
	v_add_f32_e32 v158, v22, v158
	v_exp_f32_e32 v26, v26
	v_fmamk_f32 v27, v27, 0x3e16c740, v157
	v_add_f32_e32 v158, v23, v158
	v_exp_f32_e32 v27, v27
	v_fmamk_f32 v28, v28, 0x3e16c740, v157
	v_add_f32_e32 v158, v24, v158
	v_exp_f32_e32 v28, v28
	v_fmamk_f32 v29, v29, 0x3e16c740, v157
	v_add_f32_e32 v158, v25, v158
	v_exp_f32_e32 v29, v29
	v_fmamk_f32 v30, v30, 0x3e16c740, v157
	v_add_f32_e32 v158, v26, v158
	v_exp_f32_e32 v30, v30
	v_fmamk_f32 v31, v31, 0x3e16c740, v157
	v_add_f32_e32 v158, v27, v158
	v_exp_f32_e32 v31, v31
	v_fmamk_f32 v32, v32, 0x3e16c740, v157
	v_add_f32_e32 v158, v28, v158
	v_exp_f32_e32 v32, v32
	v_fmamk_f32 v33, v33, 0x3e16c740, v157
	v_add_f32_e32 v158, v29, v158
	v_exp_f32_e32 v33, v33
	v_fmamk_f32 v2, v2, 0x3e16c740, v157
	v_add_f32_e32 v158, v30, v158
	v_exp_f32_e32 v159, v2
	v_add_f32_e32 v158, v31, v158
	v_add_f32_e32 v158, v32, v158
	v_add_f32_e32 v158, v33, v158
	v_fmamk_f32 v3, v3, 0x3e16c740, v157
	v_add_f32_e32 v2, v159, v158
	v_exp_f32_e32 v158, v3
	v_fmamk_f32 v3, v4, 0x3e16c740, v157
	v_exp_f32_e32 v160, v3
	v_fmamk_f32 v3, v5, 0x3e16c740, v157
	v_exp_f32_e32 v161, v3
	v_fmamk_f32 v3, v6, 0x3e16c740, v157
	v_exp_f32_e32 v162, v3
	v_fmamk_f32 v3, v7, 0x3e16c740, v157
	v_add_f32_e32 v2, v158, v2
	v_exp_f32_e32 v164, v3
	v_fmamk_f32 v3, v8, 0x3e16c740, v157
	v_add_f32_e32 v2, v160, v2
	v_exp_f32_e32 v165, v3
	v_fmamk_f32 v3, v9, 0x3e16c740, v157
	v_add_f32_e32 v2, v161, v2
	v_exp_f32_e32 v166, v3
	v_fmamk_f32 v3, v10, 0x3e16c740, v157
	v_add_f32_e32 v2, v162, v2
	v_exp_f32_e32 v167, v3
	v_fmamk_f32 v3, v11, 0x3e16c740, v157
	v_add_f32_e32 v2, v164, v2
	v_exp_f32_e32 v182, v3
	v_fmamk_f32 v3, v12, 0x3e16c740, v157
	v_add_f32_e32 v2, v165, v2
	v_exp_f32_e32 v183, v3
	v_fmamk_f32 v3, v13, 0x3e16c740, v157
	v_add_f32_e32 v2, v166, v2
	v_exp_f32_e32 v184, v3
	v_fmamk_f32 v3, v14, 0x3e16c740, v157
	v_add_f32_e32 v2, v167, v2
	v_exp_f32_e32 v14, v3
	v_fmamk_f32 v3, v15, 0x3e16c740, v157
	v_add_f32_e32 v2, v182, v2
	v_exp_f32_e32 v15, v3
	v_fmamk_f32 v3, v16, 0x3e16c740, v157
	v_add_f32_e32 v2, v183, v2
	v_exp_f32_e32 v16, v3
	v_fmac_f32_e32 v157, 0x3e16c740, v17
	v_add_f32_e32 v2, v184, v2
	v_exp_f32_e32 v17, v157
	v_add_f32_e32 v2, v14, v2
	v_add_f32_e32 v2, v15, v2
	v_add_f32_e32 v2, v16, v2
	v_add_f32_e32 v2, v17, v2
	v_add_f32_e32 v0, v2, v0
	v_cvt_pk_bf16_f32 v2, v18, v19
	s_nop 1
	v_cvt_pk_bf16_f32 v3, v20, v21
	s_nop 1
	v_cvt_pk_bf16_f32 v4, v22, v23
	s_nop 1
	v_cvt_pk_bf16_f32 v5, v24, v25
	s_nop 1
	s_waitcnt lgkmcnt(7)
	v_mfma_f32_32x32x16_bf16 v[34:49], v[220:223], v[2:5], v[34:49]
	s_waitcnt lgkmcnt(5)
	v_mfma_f32_32x32x16_bf16 v[50:65], v[228:231], v[2:5], v[50:65]
	v_cvt_pk_bf16_f32 v2, v26, v27
	s_nop 1
	v_cvt_pk_bf16_f32 v3, v28, v29
	s_nop 1
	v_cvt_pk_bf16_f32 v4, v30, v31
	s_nop 1
	v_cvt_pk_bf16_f32 v5, v32, v33
	s_nop 1
	s_waitcnt lgkmcnt(4)
	v_mfma_f32_32x32x16_bf16 v[50:65], v[232:235], v[2:5], v[50:65]
	v_mfma_f32_32x32x16_bf16 v[34:49], v[224:227], v[2:5], v[34:49]
	v_cvt_pk_bf16_f32 v2, v159, v158
	s_nop 1
	v_cvt_pk_bf16_f32 v3, v160, v161
	s_nop 1
	v_cvt_pk_bf16_f32 v4, v162, v164
	s_nop 1
	v_cvt_pk_bf16_f32 v5, v165, v166
	s_nop 1
	v_mov_b32_e32 v158, v142
	s_waitcnt lgkmcnt(3)
	v_mfma_f32_32x32x16_bf16 v[34:49], v[236:239], v[2:5], v[34:49]
	s_waitcnt lgkmcnt(2)
	v_mfma_f32_32x32x16_bf16 v[50:65], v[240:243], v[2:5], v[50:65]
	v_cvt_pk_bf16_f32 v2, v167, v182
	s_nop 1
	v_cvt_pk_bf16_f32 v3, v183, v184
	s_nop 1
	v_cvt_pk_bf16_f32 v4, v14, v15
	s_nop 1
	v_cvt_pk_bf16_f32 v5, v16, v17
	s_nop 1
	s_waitcnt lgkmcnt(1)
	v_mfma_f32_32x32x16_bf16 v[34:49], v[244:247], v[2:5], v[34:49]
	s_waitcnt lgkmcnt(0)
	v_mfma_f32_32x32x16_bf16 v[50:65], v[248:251], v[2:5], v[50:65]
.LBB0_262:
	s_or_b64 exec, exec, s[24:25]
	s_nop 7
	s_nop 0
	v_mov_b64_e32 v[18:19], v[34:35]
	s_nop 1
	v_mov_b64_e32 v[2:3], v[50:51]
	v_mov_b64_e32 v[20:21], v[36:37]
	v_mov_b64_e32 v[22:23], v[38:39]
	v_mov_b64_e32 v[24:25], v[40:41]
	v_mov_b64_e32 v[26:27], v[42:43]
	v_mov_b64_e32 v[28:29], v[44:45]
	v_mov_b64_e32 v[30:31], v[46:47]
	v_mov_b64_e32 v[32:33], v[48:49]
	v_mov_b64_e32 v[4:5], v[52:53]
	v_mov_b64_e32 v[6:7], v[54:55]
	v_mov_b64_e32 v[8:9], v[56:57]
	v_mov_b64_e32 v[10:11], v[58:59]
	v_mov_b64_e32 v[12:13], v[60:61]
	v_mov_b64_e32 v[14:15], v[62:63]
	v_mov_b64_e32 v[16:17], v[64:65]
	v_mov_b32_e32 v142, v0
	v_mov_b32_e32 v157, v158
	s_andn2_b64 vcc, exec, s[22:23]
	s_cbranch_vccz .LBB0_254
	s_branch .LBB0_255

; #define MFMA32(a, b, c) __builtin_amdgcn_mfma_f32_32x32x16_bf16((a), (b), (c), 0, 0, 0)
; template <int DQK, bool WIN>
; DI void attn_item(const u16* __restrict__ Qb, int ldq, const u16* __restrict__ Kb, int ldk, const u16* __restrict__ Vtb, int qb,
;                   float qscale, float sink2, const u16* __restrict__ zb, int ldz, u16* __restrict__ ob, int ldo, u16* lds) {
;     ...
;       for (int kb = 0; kb < 2; ++kb) {
; #pragma unroll
;         for (int i = 0; i < 16; ++i) st[kb][i] = 0.f;
; #pragma unroll
;         for (int s = 0; s < NKS; ++s) {
;           bf16x8 a = *(const bf16x8*)(ks + (kb * 32 + r) * KST + 16 * s + 8 * hh);
;           st[kb] = MFMA32(a, qf[s], st[kb]);
;         }
;       }
;       float mx = -INFINITY;
; #pragma unroll
;       for (int kb = 0; kb < 2; ++kb)
; #pragma unroll
;         for (int i = 0; i < 16; ++i) {
;           float v = st[kb][i];
;           if (MASK) {
;             int kg = k0 + kb * 32 + (i & 3) + 8 * (i >> 2) + 4 * hh;
;             bool ok = kg <= qrow;
;             if (WIN) ok = ok && (qrow - kg < 128);
;             v = ok ? v : -INFINITY;
;             st[kb][i] = v;
;           }
;           mx = fmaxf(mx, v);
;         }
.LBB0_317:
	s_add_i32 s0, s26, 0xffffff40
	v_cmp_le_i32_e32 vcc, s0, v137
	s_add_i32 s0, s26, 0xffffff7f
	v_cmp_ge_i32_e64 s[8:9], s0, v138
	s_and_b64 s[0:1], vcc, s[8:9]
	v_add_u32_e32 v143, s26, v0
	s_and_saveexec_b64 s[34:35], s[0:1]
	s_cbranch_execz .LBB0_321
	ds_read_b128 v[220:223], v139
	ds_read_b128 v[224:227], v139 offset:32
	ds_read_b128 v[228:231], v139 offset:64
	ds_read_b128 v[232:235], v139 offset:4640
	ds_read_b128 v[236:239], v139 offset:96
	ds_read_b128 v[240:243], v139 offset:4608
	ds_read_b128 v[244:247], v139 offset:4672
	ds_read_b128 v[248:251], v139 offset:4704
	v_add_u32_e32 v145, 0xffffff40, v143
	v_cmp_le_i32_e64 s[8:9], v145, v114
	s_movk_i32 s0, 0xff7f
	s_waitcnt lgkmcnt(7)
	v_mfma_f32_32x32x16_bf16 v[50:65], v[220:223], v[66:69], 0
	s_waitcnt lgkmcnt(6)
	v_mfma_f32_32x32x16_bf16 v[50:65], v[224:227], v[70:73], v[50:65]
	s_waitcnt lgkmcnt(5)
	v_mfma_f32_32x32x16_bf16 v[50:65], v[228:231], v[74:77], v[50:65]
	s_waitcnt lgkmcnt(3)
	v_mfma_f32_32x32x16_bf16 v[50:65], v[236:239], v[78:81], v[50:65]
	s_waitcnt lgkmcnt(2)
	v_mfma_f32_32x32x16_bf16 v[34:49], v[240:243], v[66:69], 0
	v_mfma_f32_32x32x16_bf16 v[34:49], v[232:235], v[70:73], v[34:49]
	s_waitcnt lgkmcnt(1)
	v_mfma_f32_32x32x16_bf16 v[34:49], v[244:247], v[74:77], v[34:49]
	s_waitcnt lgkmcnt(0)
	v_mfma_f32_32x32x16_bf16 v[34:49], v[248:251], v[78:81], v[34:49]
	v_add_u32_e32 v146, 59, v141
	v_cmp_gt_i32_e32 vcc, s93, v146
	s_and_b64 vcc, s[8:9], vcc
	v_add_u32_e32 v146, 0xffffff42, v143
	s_nop 0
	v_cndmask_b32_e32 v50, v176, v50, vcc
	v_cmp_lt_i32_e32 vcc, v145, v114
	v_add_u32_e32 v145, s26, v142
	v_add_u32_e32 v145, 0xffffff40, v145
	v_cmp_lt_i32_e64 s[8:9], s0, v145
	s_and_b64 vcc, vcc, s[8:9]
	v_add_u32_e32 v147, 57, v141
	v_cndmask_b32_e32 v51, v176, v51, vcc
	v_cmp_gt_i32_e32 vcc, s93, v147
	v_cmp_le_i32_e64 s[8:9], v146, v114
	s_and_b64 vcc, s[8:9], vcc
	v_add_u32_e32 v146, 0xffffff43, v143
	v_add_u32_e32 v147, 56, v141
	v_cndmask_b32_e32 v52, v176, v52, vcc
	v_cmp_gt_i32_e32 vcc, s93, v147
	v_cmp_le_i32_e64 s[8:9], v146, v114
	s_and_b64 vcc, s[8:9], vcc
	v_add_u32_e32 v146, 0xffffff48, v143
	v_add_u32_e32 v147, 51, v141
	v_cndmask_b32_e32 v53, v176, v53, vcc
	v_cmp_gt_i32_e32 vcc, s93, v147
	v_cmp_le_i32_e64 s[8:9], v146, v114
	s_and_b64 vcc, s[8:9], vcc
	v_cndmask_b32_e32 v148, v176, v54, vcc
	v_add_u32_e32 v54, 0xffffff49, v143
	v_add_u32_e32 v146, 50, v141
	v_cmp_gt_i32_e32 vcc, s93, v146
	v_cmp_le_i32_e64 s[8:9], v54, v114
	v_max3_f32 v145, v50, s94, v51
	s_and_b64 vcc, s[8:9], vcc
	v_max3_f32 v145, v145, v52, v53
	v_cndmask_b32_e32 v147, v176, v55, vcc
	v_max3_f32 v54, v145, v148, v147
	v_add_u32_e32 v55, 0xffffff4a, v143
	v_add_u32_e32 v145, 49, v141
	v_cmp_gt_i32_e32 vcc, s93, v145
	v_cmp_le_i32_e64 s[8:9], v55, v114
	s_and_b64 vcc, s[8:9], vcc
	v_cndmask_b32_e32 v149, v176, v56, vcc
	v_add_u32_e32 v55, 0xffffff4b, v143
	v_add_u32_e32 v56, 48, v141
	v_cmp_gt_i32_e32 vcc, s93, v56
	v_cmp_le_i32_e64 s[8:9], v55, v114
	s_and_b64 vcc, s[8:9], vcc
	v_add_u32_e32 v55, 0xffffff50, v143
	v_add_u32_e32 v56, 43, v141
	v_cndmask_b32_e32 v150, v176, v57, vcc
	v_cmp_gt_i32_e32 vcc, s93, v56
	v_cmp_le_i32_e64 s[8:9], v55, v114
	s_and_b64 vcc, s[8:9], vcc
	v_add_u32_e32 v55, 0xffffff51, v143
	v_add_u32_e32 v56, 42, v141
	v_cndmask_b32_e32 v151, v176, v58, vcc
	v_cmp_gt_i32_e32 vcc, s93, v56
	v_cmp_le_i32_e64 s[8:9], v55, v114
	s_and_b64 vcc, s[8:9], vcc
	v_add_u32_e32 v55, 0xffffff52, v143
	v_add_u32_e32 v56, 41, v141
	v_cndmask_b32_e32 v145, v176, v59, vcc
	v_cmp_gt_i32_e32 vcc, s93, v56
	v_cmp_le_i32_e64 s[8:9], v55, v114
	s_and_b64 vcc, s[8:9], vcc
	v_add_u32_e32 v55, 0xffffff53, v143
	v_add_u32_e32 v56, 40, v141
	v_cndmask_b32_e32 v146, v176, v60, vcc
	v_cmp_gt_i32_e32 vcc, s93, v56
	v_cmp_le_i32_e64 s[8:9], v55, v114
	s_and_b64 vcc, s[8:9], vcc
	v_add_u32_e32 v55, 0xffffff58, v143
	v_add_u32_e32 v56, 35, v141
	v_cndmask_b32_e32 v60, v176, v61, vcc
	v_cmp_gt_i32_e32 vcc, s93, v56
	v_cmp_le_i32_e64 s[8:9], v55, v114
	s_and_b64 vcc, s[8:9], vcc
	v_add_u32_e32 v55, 0xffffff59, v143
	v_add_u32_e32 v56, 34, v141
	v_cndmask_b32_e32 v61, v176, v62, vcc
	v_cmp_gt_i32_e32 vcc, s93, v56
	v_cmp_le_i32_e64 s[8:9], v55, v114
	s_and_b64 vcc, s[8:9], vcc
	v_add_u32_e32 v55, 0xffffff5a, v143
	v_add_u32_e32 v56, 33, v141
	v_cndmask_b32_e32 v58, v176, v63, vcc
	v_cmp_gt_i32_e32 vcc, s93, v56
	v_cmp_le_i32_e64 s[8:9], v55, v114
	v_max3_f32 v54, v54, v149, v150
	s_and_b64 vcc, s[8:9], vcc
	v_add_u32_e32 v55, 0xffffff5b, v143
	v_add_u32_e32 v56, 32, v141
	v_max3_f32 v54, v54, v151, v145
	v_cndmask_b32_e32 v59, v176, v64, vcc
	v_cmp_gt_i32_e32 vcc, s93, v56
	v_cmp_le_i32_e64 s[8:9], v55, v114
	v_max3_f32 v54, v54, v146, v60
	s_and_b64 vcc, s[8:9], vcc
	v_max3_f32 v54, v54, v61, v58
	v_cndmask_b32_e32 v56, v176, v65, vcc
	v_max3_f32 v55, v54, v59, v56
	v_add_u32_e32 v54, 0xffffff60, v143
	v_add_u32_e32 v57, 27, v141
	v_cmp_gt_i32_e32 vcc, s93, v57
	v_cmp_le_i32_e64 s[8:9], v54, v114
	s_and_b64 vcc, s[8:9], vcc
	v_cndmask_b32_e32 v57, v176, v34, vcc
	v_add_u32_e32 v34, 0xffffff61, v143
	v_add_u32_e32 v54, 26, v141
	v_cmp_gt_i32_e32 vcc, s93, v54
	v_cmp_le_i32_e64 s[8:9], v34, v114
	s_and_b64 vcc, s[8:9], vcc
	v_cndmask_b32_e32 v54, v176, v35, vcc
	v_max3_f32 v34, v55, v57, v54
	v_add_u32_e32 v35, 0xffffff62, v143
	v_add_u32_e32 v55, 25, v141
	v_cmp_gt_i32_e32 vcc, s93, v55
	v_cmp_le_i32_e64 s[8:9], v35, v114
	s_and_b64 vcc, s[8:9], vcc
	v_cndmask_b32_e32 v55, v176, v36, vcc
	v_add_u32_e32 v35, 0xffffff63, v143
	v_add_u32_e32 v36, 24, v141
	v_cmp_gt_i32_e32 vcc, s93, v36
	v_cmp_le_i32_e64 s[8:9], v35, v114
	s_and_b64 vcc, s[8:9], vcc
	v_cndmask_b32_e32 v36, v176, v37, vcc
; template <int DQK, bool WIN>
; DI void attn_item(const u16* __restrict__ Qb, int ldq, const u16* __restrict__ Kb, int ldk, const u16* __restrict__ Vtb, int qb,
;                   float qscale, float sink2, const u16* __restrict__ zb, int ldz, u16* __restrict__ ob, int ldo, u16* lds) {
;     ...
;       float mx = -INFINITY;
; #pragma unroll
;       for (int kb = 0; kb < 2; ++kb)
; #pragma unroll
;         for (int i = 0; i < 16; ++i) {
;           float v = st[kb][i];
;           if (MASK) {
;             int kg = k0 + kb * 32 + (i & 3) + 8 * (i >> 2) + 4 * hh;
;             bool ok = kg <= qrow;
;             if (WIN) ok = ok && (qrow - kg < 128);
;             v = ok ? v : -INFINITY;
;             st[kb][i] = v;
;           }
;           mx = fmaxf(mx, v);
;         }
;       mx = fmaxf(mx, __shfl_xor(mx, 32));
;       const float mn = fmaxf(m, mx);
;       if (__any(mn != m)) {
;         const float alpha = __builtin_amdgcn_exp2f((m - mn) * qscale);
;         lsum *= alpha;
; #pragma unroll
;         for (int i = 0; i < 16; ++i) { o[0][i] *= alpha; o[1][i] *= alpha; }
;       }
	v_add_u32_e32 v35, 0xffffff68, v143
	v_add_u32_e32 v37, 19, v141
	v_cmp_gt_i32_e32 vcc, s93, v37
	v_cmp_le_i32_e64 s[8:9], v35, v114
	s_and_b64 vcc, s[8:9], vcc
	v_cndmask_b32_e32 v37, v176, v38, vcc
	v_add_u32_e32 v35, 0xffffff69, v143
	v_add_u32_e32 v38, 18, v141
	v_cmp_gt_i32_e32 vcc, s93, v38
	v_cmp_le_i32_e64 s[8:9], v35, v114
	s_and_b64 vcc, s[8:9], vcc
	v_cndmask_b32_e32 v35, v176, v39, vcc
	v_add_u32_e32 v38, 0xffffff6a, v143
	v_add_u32_e32 v39, 17, v141
	v_cmp_gt_i32_e32 vcc, s93, v39
	v_cmp_le_i32_e64 s[8:9], v38, v114
	s_and_b64 vcc, s[8:9], vcc
	v_cndmask_b32_e32 v38, v176, v40, vcc
	v_add_u32_e32 v39, 0xffffff6b, v143
	v_add_u32_e32 v40, 16, v141
	v_cmp_gt_i32_e32 vcc, s93, v40
	v_cmp_le_i32_e64 s[8:9], v39, v114
	s_and_b64 vcc, s[8:9], vcc
	v_cndmask_b32_e32 v39, v176, v41, vcc
	v_add_u32_e32 v40, 0xffffff70, v143
	v_add_u32_e32 v41, 11, v141
	v_cmp_gt_i32_e32 vcc, s93, v41
	v_cmp_le_i32_e64 s[8:9], v40, v114
	s_and_b64 vcc, s[8:9], vcc
	v_cndmask_b32_e32 v40, v176, v42, vcc
	v_add_u32_e32 v41, 0xffffff71, v143
	v_add_u32_e32 v42, 10, v141
	v_cmp_gt_i32_e32 vcc, s93, v42
	v_cmp_le_i32_e64 s[8:9], v41, v114
	s_and_b64 vcc, s[8:9], vcc
	v_cndmask_b32_e32 v41, v176, v43, vcc
	v_add_u32_e32 v42, 0xffffff72, v143
	v_add_u32_e32 v43, 9, v141
	v_cmp_gt_i32_e32 vcc, s93, v43
	v_cmp_le_i32_e64 s[8:9], v42, v114
	s_and_b64 vcc, s[8:9], vcc
	v_cndmask_b32_e32 v42, v176, v44, vcc
	v_add_u32_e32 v43, 0xffffff73, v143
	v_add_u32_e32 v44, 8, v141
	v_cmp_gt_i32_e32 vcc, s93, v44
	v_cmp_le_i32_e64 s[8:9], v43, v114
	s_and_b64 vcc, s[8:9], vcc
	v_cndmask_b32_e32 v43, v176, v45, vcc
	v_add_u32_e32 v44, 0xffffff78, v143
	v_add_u32_e32 v45, 3, v141
	v_cmp_gt_i32_e32 vcc, s93, v45
	v_cmp_le_i32_e64 s[8:9], v44, v114
	s_and_b64 vcc, s[8:9], vcc
	v_cndmask_b32_e32 v44, v176, v46, vcc
	v_add_u32_e32 v45, 0xffffff79, v143
	v_add_u32_e32 v46, 2, v141
	v_cmp_gt_i32_e32 vcc, s93, v46
	v_cmp_le_i32_e64 s[8:9], v45, v114
	s_and_b64 vcc, s[8:9], vcc
	v_cndmask_b32_e32 v45, v176, v47, vcc
	v_add_u32_e32 v46, 0xffffff7a, v143
	v_add_u32_e32 v47, 1, v141
	v_cmp_gt_i32_e32 vcc, s93, v47
	v_cmp_le_i32_e64 s[8:9], v46, v114
	s_and_b64 vcc, s[8:9], vcc
	v_add_u32_e32 v47, 0xffffff7b, v143
	v_max3_f32 v34, v34, v55, v36
	v_cndmask_b32_e32 v46, v176, v48, vcc
	v_cmp_gt_i32_e32 vcc, s93, v141
	v_cmp_le_i32_e64 s[8:9], v47, v114
	v_max3_f32 v34, v34, v37, v35
	s_and_b64 vcc, s[8:9], vcc
	v_max3_f32 v34, v34, v38, v39
	v_cndmask_b32_e32 v47, v176, v49, vcc
	v_and_b32_e32 v49, 64, v172
	v_max3_f32 v34, v34, v40, v41
	v_xor_b32_e32 v48, 32, v172
	v_add_u32_e32 v49, 64, v49
	v_max3_f32 v34, v34, v42, v43
	v_cmp_lt_i32_e32 vcc, v48, v49
	v_max3_f32 v34, v34, v44, v45
	v_max3_f32 v34, v34, v46, v47
	v_cndmask_b32_e32 v48, v172, v48, vcc
	v_lshlrev_b32_e32 v48, 2, v48
	ds_bpermute_b32 v48, v48, v34
	s_waitcnt lgkmcnt(0)
	v_max3_f32 v34, v144, v34, v48
	v_cmp_neq_f32_e32 vcc, v34, v144
	s_cbranch_vccz .LBB0_320
	v_sub_f32_e32 v48, v144, v34
	v_mul_f32_e32 v48, 0x3e38aa3b, v48
	v_exp_f32_e32 v48, v48
	s_nop 0
	v_mul_f32_e32 v116, v116, v48
	v_pk_mul_f32 v[32:33], v[32:33], v[48:49] op_sel_hi:[1,0]
	v_pk_mul_f32 v[30:31], v[30:31], v[48:49] op_sel_hi:[1,0]
	v_pk_mul_f32 v[28:29], v[28:29], v[48:49] op_sel_hi:[1,0]
	v_pk_mul_f32 v[26:27], v[26:27], v[48:49] op_sel_hi:[1,0]
	v_pk_mul_f32 v[24:25], v[24:25], v[48:49] op_sel_hi:[1,0]
	v_pk_mul_f32 v[22:23], v[22:23], v[48:49] op_sel_hi:[1,0]
	v_pk_mul_f32 v[20:21], v[20:21], v[48:49] op_sel_hi:[1,0]
	v_pk_mul_f32 v[18:19], v[18:19], v[48:49] op_sel_hi:[1,0]
	v_pk_mul_f32 v[16:17], v[16:17], v[48:49] op_sel_hi:[1,0]
	v_pk_mul_f32 v[14:15], v[14:15], v[48:49] op_sel_hi:[1,0]
	v_pk_mul_f32 v[12:13], v[12:13], v[48:49] op_sel_hi:[1,0]
	v_pk_mul_f32 v[10:11], v[10:11], v[48:49] op_sel_hi:[1,0]
	v_pk_mul_f32 v[8:9], v[8:9], v[48:49] op_sel_hi:[1,0]
	v_pk_mul_f32 v[6:7], v[6:7], v[48:49] op_sel_hi:[1,0]
	v_pk_mul_f32 v[4:5], v[4:5], v[48:49] op_sel_hi:[1,0]
	v_pk_mul_f32 v[2:3], v[2:3], v[48:49] op_sel_hi:[1,0]
; DI unsigned pack2(float a, float b) { unsigned r; asm("v_cvt_pk_bf16_f32 %0, %1, %2\n\ts_nop 1" : "=v"(r) : "v"(a), "v"(b)); return r; }
; #define MFMA32(a, b, c) __builtin_amdgcn_mfma_f32_32x32x16_bf16((a), (b), (c), 0, 0, 0)
; template <int DQK, bool WIN>
; DI void attn_item(const u16* __restrict__ Qb, int ldq, const u16* __restrict__ Kb, int ldk, const u16* __restrict__ Vtb, int qb,
;                   float qscale, float sink2, const u16* __restrict__ zb, int ldz, u16* __restrict__ ob, int ldo, u16* lds) {
;     ...
;       const float nb = -mn * qscale;
;       float ps = 0.f;
; #pragma unroll
;       for (int kb = 0; kb < 2; ++kb)
; #pragma unroll
;         for (int i = 0; i < 16; ++i) { float pv = __builtin_amdgcn_exp2f(fmaf(st[kb][i], qscale, nb)); st[kb][i] = pv; ps += pv; }
;       lsum += ps;
; #pragma unroll
;       for (int kb = 0; kb < 2; ++kb)
; #pragma unroll
;         for (int s2 = 0; s2 < 2; ++s2) {
;           union { bf16x8 v; unsigned u[4]; } pf;
; #pragma unroll
;           for (int j = 0; j < 4; ++j) pf.u[j] = pack2(st[kb][8 * s2 + 2 * j], st[kb][8 * s2 + 2 * j + 1]);
; #pragma unroll
;           for (int vb = 0; vb < 2; ++vb) {
;             const bf16x8 vf = *(const bf16x8*)(vs + (vb * 32 + r) * 72 + (kb * 2 + s2) * 16 + hh * 8);
;             o[vb] = MFMA32(vf, pf.v, o[vb]);
;           }
;         }
.LBB0_320:
	ds_read_b128 v[220:223], v140 offset:9216
	ds_read_b128 v[224:227], v140 offset:13824
	ds_read_b128 v[228:231], v140 offset:13856
	ds_read_b128 v[232:235], v140 offset:9280
	ds_read_b128 v[236:239], v140 offset:13888
	ds_read_b128 v[240:243], v140 offset:9312
	v_mul_f32_e32 v48, 0xbe38aa3b, v34
	v_fmamk_f32 v49, v50, 0x3e38aa3b, v48
	v_exp_f32_e32 v49, v49
	v_fmamk_f32 v51, v51, 0x3e38aa3b, v48
	v_exp_f32_e32 v51, v51
	v_fmamk_f32 v52, v52, 0x3e38aa3b, v48
	v_exp_f32_e32 v52, v52
	v_fmamk_f32 v53, v53, 0x3e38aa3b, v48
	v_exp_f32_e32 v53, v53
	v_fmamk_f32 v62, v148, 0x3e38aa3b, v48
	v_add_f32_e32 v50, 0, v49
	v_exp_f32_e32 v62, v62
	v_fmamk_f32 v63, v147, 0x3e38aa3b, v48
	v_add_f32_e32 v50, v51, v50
	v_exp_f32_e32 v63, v63
	v_fmamk_f32 v64, v149, 0x3e38aa3b, v48
	v_add_f32_e32 v50, v52, v50
	v_exp_f32_e32 v64, v64
	v_fmamk_f32 v65, v150, 0x3e38aa3b, v48
	v_add_f32_e32 v50, v53, v50
	v_exp_f32_e32 v65, v65
	v_fmamk_f32 v144, v151, 0x3e38aa3b, v48
	v_add_f32_e32 v50, v62, v50
	v_exp_f32_e32 v144, v144
	v_fmamk_f32 v145, v145, 0x3e38aa3b, v48
	v_add_f32_e32 v50, v63, v50
	v_exp_f32_e32 v145, v145
	v_fmamk_f32 v146, v146, 0x3e38aa3b, v48
	v_add_f32_e32 v50, v64, v50
	v_exp_f32_e32 v146, v146
	v_fmamk_f32 v60, v60, 0x3e38aa3b, v48
	v_add_f32_e32 v50, v65, v50
	v_exp_f32_e32 v60, v60
	v_fmamk_f32 v61, v61, 0x3e38aa3b, v48
	v_add_f32_e32 v50, v144, v50
	v_exp_f32_e32 v61, v61
	v_fmamk_f32 v58, v58, 0x3e38aa3b, v48
	v_add_f32_e32 v50, v145, v50
	v_exp_f32_e32 v58, v58
	v_fmamk_f32 v59, v59, 0x3e38aa3b, v48
	v_add_f32_e32 v50, v146, v50
	v_exp_f32_e32 v59, v59
	v_fmamk_f32 v56, v56, 0x3e38aa3b, v48
	v_add_f32_e32 v50, v60, v50
	v_exp_f32_e32 v56, v56
	v_fmamk_f32 v57, v57, 0x3e38aa3b, v48
	v_add_f32_e32 v50, v61, v50
	v_exp_f32_e32 v57, v57
	v_fmamk_f32 v54, v54, 0x3e38aa3b, v48
	v_add_f32_e32 v50, v58, v50
	v_exp_f32_e32 v54, v54
	v_fmamk_f32 v55, v55, 0x3e38aa3b, v48
	v_add_f32_e32 v50, v59, v50
	v_exp_f32_e32 v55, v55
	v_fmamk_f32 v36, v36, 0x3e38aa3b, v48
	v_add_f32_e32 v50, v56, v50
	v_exp_f32_e32 v147, v36
	v_add_f32_e32 v50, v57, v50
	v_add_f32_e32 v50, v54, v50
	v_add_f32_e32 v50, v55, v50
	v_fmamk_f32 v37, v37, 0x3e38aa3b, v48
	v_add_f32_e32 v36, v147, v50
	v_exp_f32_e32 v50, v37
	v_fmamk_f32 v35, v35, 0x3e38aa3b, v48
	v_exp_f32_e32 v35, v35
	v_fmamk_f32 v37, v38, 0x3e38aa3b, v48
	v_exp_f32_e32 v148, v37
	v_fmamk_f32 v37, v39, 0x3e38aa3b, v48
	v_exp_f32_e32 v149, v37
	v_fmamk_f32 v37, v40, 0x3e38aa3b, v48
	v_add_f32_e32 v36, v50, v36
	v_exp_f32_e32 v150, v37
	v_fmamk_f32 v37, v41, 0x3e38aa3b, v48
	v_add_f32_e32 v36, v35, v36
	v_exp_f32_e32 v151, v37
	v_fmamk_f32 v37, v42, 0x3e38aa3b, v48
	v_add_f32_e32 v36, v148, v36
	v_exp_f32_e32 v152, v37
	v_fmamk_f32 v37, v43, 0x3e38aa3b, v48
	v_add_f32_e32 v36, v149, v36
	v_exp_f32_e32 v153, v37
	v_fmamk_f32 v37, v44, 0x3e38aa3b, v48
	v_add_f32_e32 v36, v150, v36
	v_exp_f32_e32 v154, v37
	v_fmamk_f32 v37, v45, 0x3e38aa3b, v48
	v_add_f32_e32 v36, v151, v36
	v_exp_f32_e32 v155, v37
	v_fmamk_f32 v37, v46, 0x3e38aa3b, v48
	v_add_f32_e32 v36, v152, v36
	v_exp_f32_e32 v156, v37
	v_fmac_f32_e32 v48, 0x3e38aa3b, v47
	v_add_f32_e32 v36, v153, v36
	v_exp_f32_e32 v48, v48
	v_add_f32_e32 v36, v154, v36
	ds_read_b128 v[44:47], v140 offset:9248
	v_add_f32_e32 v36, v155, v36
	v_add_f32_e32 v36, v156, v36
	v_add_f32_e32 v36, v48, v36
	v_add_f32_e32 v116, v36, v116
	v_cvt_pk_bf16_f32 v36, v49, v51
	s_nop 1
	v_cvt_pk_bf16_f32 v37, v52, v53
	s_nop 1
	v_cvt_pk_bf16_f32 v38, v62, v63
	s_nop 1
	v_cvt_pk_bf16_f32 v39, v64, v65
	s_nop 1
	s_waitcnt lgkmcnt(6)
	v_mfma_f32_32x32x16_bf16 v[18:33], v[220:223], v[36:39], v[18:33]
	s_waitcnt lgkmcnt(0)
	v_mfma_f32_32x32x16_bf16 v[2:17], v[224:227], v[36:39], v[2:17]
	v_cvt_pk_bf16_f32 v36, v144, v145
	s_nop 1
	v_cvt_pk_bf16_f32 v37, v146, v60
	s_nop 1
	v_cvt_pk_bf16_f32 v38, v61, v58
	s_nop 1
	v_cvt_pk_bf16_f32 v39, v59, v56
	s_nop 1
	v_mov_b32_e32 v144, v34
	s_waitcnt lgkmcnt(0)
	v_mfma_f32_32x32x16_bf16 v[2:17], v[228:231], v[36:39], v[2:17]
	v_mfma_f32_32x32x16_bf16 v[18:33], v[44:47], v[36:39], v[18:33]
	v_cvt_pk_bf16_f32 v36, v57, v54
	s_nop 1
	v_cvt_pk_bf16_f32 v37, v55, v147
	s_nop 1
	v_cvt_pk_bf16_f32 v38, v50, v35
	s_nop 1
	v_cvt_pk_bf16_f32 v39, v148, v149
	s_nop 1
	s_waitcnt lgkmcnt(0)
	v_mfma_f32_32x32x16_bf16 v[18:33], v[232:235], v[36:39], v[18:33]
	s_waitcnt lgkmcnt(0)
	v_mfma_f32_32x32x16_bf16 v[2:17], v[236:239], v[36:39], v[2:17]
	v_cvt_pk_bf16_f32 v36, v150, v151
	s_nop 1
	v_cvt_pk_bf16_f32 v37, v152, v153
	s_nop 1
	v_cvt_pk_bf16_f32 v38, v154, v155
	s_nop 1
	v_cvt_pk_bf16_f32 v39, v156, v48
	s_nop 1
	s_waitcnt lgkmcnt(0)
	v_mfma_f32_32x32x16_bf16 v[18:33], v[240:243], v[36:39], v[18:33]
	ds_read_b128 v[40:43], v140 offset:13920
	s_waitcnt lgkmcnt(0)
	v_mfma_f32_32x32x16_bf16 v[2:17], v[40:43], v[36:39], v[2:17]

; #define MFMA32(a, b, c) __builtin_amdgcn_mfma_f32_32x32x16_bf16((a), (b), (c), 0, 0, 0)
; template <int DQK, bool WIN>
; DI void attn_item(const u16* __restrict__ Qb, int ldq, const u16* __restrict__ Kb, int ldk, const u16* __restrict__ Vtb, int qb,
;                   float qscale, float sink2, const u16* __restrict__ zb, int ldz, u16* __restrict__ ob, int ldo, u16* lds) {
;     ...
;     bool active = (k0 <= q0 + 31);
;     if (WIN) active = active && (k0 + 63 >= q0 - 127);
;     if (active) {
;       f32x16 st[2];
; #pragma unroll
;       for (int kb = 0; kb < 2; ++kb) {
; #pragma unroll
;         for (int i = 0; i < 16; ++i) st[kb][i] = 0.f;
; #pragma unroll
;         for (int s = 0; s < NKS; ++s) {
;           bf16x8 a = *(const bf16x8*)(ks + (kb * 32 + r) * KST + 16 * s + 8 * hh);
;           st[kb] = MFMA32(a, qf[s], st[kb]);
;         }
;       }
;       float mx = -INFINITY;
; #pragma unroll
;       for (int kb = 0; kb < 2; ++kb)
; #pragma unroll
;         for (int i = 0; i < 16; ++i) {
;           float v = st[kb][i];
;           if (MASK) {
;             int kg = k0 + kb * 32 + (i & 3) + 8 * (i >> 2) + 4 * hh;
;             bool ok = kg <= qrow;
;             if (WIN) ok = ok && (qrow - kg < 128);
;             v = ok ? v : -INFINITY;
;             st[kb][i] = v;
;           }
;           mx = fmaxf(mx, v);
.LBB0_323:
	s_add_i32 s0, s26, 0xffffff80
	v_cmp_le_i32_e32 vcc, s0, v137
	s_add_i32 s0, s26, 0xffffffbf
	v_cmp_ge_i32_e64 s[8:9], s0, v138
	s_and_b64 s[0:1], vcc, s[8:9]
	s_and_saveexec_b64 s[34:35], s[0:1]
	s_cbranch_execz .LBB0_327
	ds_read_b128 v[220:223], v139 offset:18432
	ds_read_b128 v[224:227], v139 offset:18464
	ds_read_b128 v[228:231], v139 offset:18496
	ds_read_b128 v[232:235], v139 offset:23072
	ds_read_b128 v[236:239], v139 offset:18528
	ds_read_b128 v[240:243], v139 offset:23040
	ds_read_b128 v[244:247], v139 offset:23104
	ds_read_b128 v[248:251], v139 offset:23136
	v_add_u32_e32 v145, 0xffffff80, v143
	v_cmp_le_i32_e64 s[8:9], v145, v114
	v_add_u32_e32 v145, 0xffffff81, v143
	s_waitcnt lgkmcnt(7)
	v_mfma_f32_32x32x16_bf16 v[50:65], v[220:223], v[66:69], 0
	s_waitcnt lgkmcnt(6)
	v_mfma_f32_32x32x16_bf16 v[50:65], v[224:227], v[70:73], v[50:65]
	s_waitcnt lgkmcnt(5)
	v_mfma_f32_32x32x16_bf16 v[50:65], v[228:231], v[74:77], v[50:65]
	s_waitcnt lgkmcnt(3)
	v_mfma_f32_32x32x16_bf16 v[50:65], v[236:239], v[78:81], v[50:65]
	s_waitcnt lgkmcnt(2)
	v_mfma_f32_32x32x16_bf16 v[34:49], v[240:243], v[66:69], 0
	v_mfma_f32_32x32x16_bf16 v[34:49], v[232:235], v[70:73], v[34:49]
	s_waitcnt lgkmcnt(1)
	v_mfma_f32_32x32x16_bf16 v[34:49], v[244:247], v[74:77], v[34:49]
	s_waitcnt lgkmcnt(0)
	v_mfma_f32_32x32x16_bf16 v[34:49], v[248:251], v[78:81], v[34:49]
	v_add_u32_e32 v146, -5, v141
	v_cmp_gt_i32_e32 vcc, s93, v146
	s_and_b64 vcc, s[8:9], vcc
	v_add_u32_e32 v146, -6, v141
	s_nop 0
	v_cndmask_b32_e32 v50, v176, v50, vcc
	v_cmp_gt_i32_e32 vcc, s93, v146
	v_cmp_le_i32_e64 s[8:9], v145, v114
	s_and_b64 vcc, s[8:9], vcc
	v_add_u32_e32 v146, 0xffffff82, v143
	v_add_u32_e32 v147, -7, v141
	v_cndmask_b32_e32 v51, v176, v51, vcc
	v_cmp_gt_i32_e32 vcc, s93, v147
	v_cmp_le_i32_e64 s[8:9], v146, v114
	s_and_b64 vcc, s[8:9], vcc
	v_add_u32_e32 v146, 0xffffff83, v143
	v_add_u32_e32 v147, -8, v141
	v_cndmask_b32_e32 v52, v176, v52, vcc
	v_cmp_gt_i32_e32 vcc, s93, v147
	v_cmp_le_i32_e64 s[8:9], v146, v114
	s_and_b64 vcc, s[8:9], vcc
	v_add_u32_e32 v146, 0xffffff88, v143
	v_add_u32_e32 v147, -13, v141
	v_cndmask_b32_e32 v53, v176, v53, vcc
	v_cmp_gt_i32_e32 vcc, s93, v147
	v_cmp_le_i32_e64 s[8:9], v146, v114
	s_and_b64 vcc, s[8:9], vcc
	v_cndmask_b32_e32 v148, v176, v54, vcc
	v_add_u32_e32 v54, 0xffffff89, v143
	v_add_u32_e32 v146, -14, v141
	v_cmp_gt_i32_e32 vcc, s93, v146
	v_cmp_le_i32_e64 s[8:9], v54, v114
	v_max3_f32 v145, v50, s94, v51
	s_and_b64 vcc, s[8:9], vcc
	v_max3_f32 v145, v145, v52, v53
	v_cndmask_b32_e32 v147, v176, v55, vcc
	v_max3_f32 v54, v145, v148, v147
	v_add_u32_e32 v55, 0xffffff8a, v143
	v_add_u32_e32 v145, -15, v141
	v_cmp_gt_i32_e32 vcc, s93, v145
	v_cmp_le_i32_e64 s[8:9], v55, v114
	s_and_b64 vcc, s[8:9], vcc
	v_cndmask_b32_e32 v149, v176, v56, vcc
	v_add_u32_e32 v55, 0xffffff8b, v143
	v_add_u32_e32 v56, -16, v141
	v_cmp_gt_i32_e32 vcc, s93, v56
	v_cmp_le_i32_e64 s[8:9], v55, v114
	s_and_b64 vcc, s[8:9], vcc
	v_add_u32_e32 v55, 0xffffff90, v143
	v_subrev_u32_e32 v56, 21, v141
	v_cndmask_b32_e32 v150, v176, v57, vcc
	v_cmp_gt_i32_e32 vcc, s93, v56
	v_cmp_le_i32_e64 s[8:9], v55, v114
	s_and_b64 vcc, s[8:9], vcc
	v_add_u32_e32 v55, 0xffffff91, v143
	v_subrev_u32_e32 v56, 22, v141
	v_cndmask_b32_e32 v151, v176, v58, vcc
	v_cmp_gt_i32_e32 vcc, s93, v56
	v_cmp_le_i32_e64 s[8:9], v55, v114
	s_and_b64 vcc, s[8:9], vcc
	v_add_u32_e32 v55, 0xffffff92, v143
	v_subrev_u32_e32 v56, 23, v141
	v_cndmask_b32_e32 v145, v176, v59, vcc
	v_cmp_gt_i32_e32 vcc, s93, v56
	v_cmp_le_i32_e64 s[8:9], v55, v114
	s_and_b64 vcc, s[8:9], vcc
	v_add_u32_e32 v55, 0xffffff93, v143
	v_subrev_u32_e32 v56, 24, v141
	v_cndmask_b32_e32 v146, v176, v60, vcc
	v_cmp_gt_i32_e32 vcc, s93, v56
	v_cmp_le_i32_e64 s[8:9], v55, v114
	s_and_b64 vcc, s[8:9], vcc
	v_add_u32_e32 v55, 0xffffff98, v143
	v_subrev_u32_e32 v56, 29, v141
	v_cndmask_b32_e32 v60, v176, v61, vcc
	v_cmp_gt_i32_e32 vcc, s93, v56
	v_cmp_le_i32_e64 s[8:9], v55, v114
	s_and_b64 vcc, s[8:9], vcc
	v_add_u32_e32 v55, 0xffffff99, v143
	v_subrev_u32_e32 v56, 30, v141
	v_cndmask_b32_e32 v61, v176, v62, vcc
	v_cmp_gt_i32_e32 vcc, s93, v56
	v_cmp_le_i32_e64 s[8:9], v55, v114
	s_and_b64 vcc, s[8:9], vcc
	v_add_u32_e32 v55, 0xffffff9a, v143
	v_subrev_u32_e32 v56, 31, v141
	v_cndmask_b32_e32 v58, v176, v63, vcc
	v_cmp_gt_i32_e32 vcc, s93, v56
	v_cmp_le_i32_e64 s[8:9], v55, v114
	v_max3_f32 v54, v54, v149, v150
	s_and_b64 vcc, s[8:9], vcc
	v_add_u32_e32 v55, 0xffffff9b, v143
	v_subrev_u32_e32 v56, 32, v141
	v_max3_f32 v54, v54, v151, v145
	v_cndmask_b32_e32 v59, v176, v64, vcc
	v_cmp_gt_i32_e32 vcc, s93, v56
	v_cmp_le_i32_e64 s[8:9], v55, v114
	v_max3_f32 v54, v54, v146, v60
	s_and_b64 vcc, s[8:9], vcc
	v_max3_f32 v54, v54, v61, v58
	v_cndmask_b32_e32 v56, v176, v65, vcc
	v_max3_f32 v55, v54, v59, v56
	v_add_u32_e32 v54, 0xffffffa0, v143
	v_subrev_u32_e32 v57, 37, v141
	v_cmp_gt_i32_e32 vcc, s93, v57
	v_cmp_le_i32_e64 s[8:9], v54, v114
	s_and_b64 vcc, s[8:9], vcc
	v_cndmask_b32_e32 v57, v176, v34, vcc
	v_add_u32_e32 v34, 0xffffffa1, v143
	v_subrev_u32_e32 v54, 38, v141
	v_cmp_gt_i32_e32 vcc, s93, v54
	v_cmp_le_i32_e64 s[8:9], v34, v114
	s_and_b64 vcc, s[8:9], vcc
	v_cndmask_b32_e32 v54, v176, v35, vcc
	v_max3_f32 v34, v55, v57, v54
	v_add_u32_e32 v35, 0xffffffa2, v143
	v_subrev_u32_e32 v55, 39, v141
	v_cmp_gt_i32_e32 vcc, s93, v55
	v_cmp_le_i32_e64 s[8:9], v35, v114
	s_and_b64 vcc, s[8:9], vcc
	v_cndmask_b32_e32 v55, v176, v36, vcc
	v_add_u32_e32 v35, 0xffffffa3, v143
	v_subrev_u32_e32 v36, 40, v141
	v_cmp_gt_i32_e32 vcc, s93, v36
	v_cmp_le_i32_e64 s[8:9], v35, v114
	s_and_b64 vcc, s[8:9], vcc
	v_cndmask_b32_e32 v36, v176, v37, vcc
; template <int DQK, bool WIN>
; DI void attn_item(const u16* __restrict__ Qb, int ldq, const u16* __restrict__ Kb, int ldk, const u16* __restrict__ Vtb, int qb,
;                   float qscale, float sink2, const u16* __restrict__ zb, int ldz, u16* __restrict__ ob, int ldo, u16* lds) {
;     ...
;           if (MASK) {
;             int kg = k0 + kb * 32 + (i & 3) + 8 * (i >> 2) + 4 * hh;
;             bool ok = kg <= qrow;
;             if (WIN) ok = ok && (qrow - kg < 128);
;             v = ok ? v : -INFINITY;
;             st[kb][i] = v;
;           }
;           mx = fmaxf(mx, v);
;         }
;       mx = fmaxf(mx, __shfl_xor(mx, 32));
;       const float mn = fmaxf(m, mx);
;       if (__any(mn != m)) {
;         const float alpha = __builtin_amdgcn_exp2f((m - mn) * qscale);
;         lsum *= alpha;
; #pragma unroll
;         for (int i = 0; i < 16; ++i) { o[0][i] *= alpha; o[1][i] *= alpha; }
;       }
;       m = mn;
	v_add_u32_e32 v35, 0xffffffa8, v143
	v_subrev_u32_e32 v37, 45, v141
	v_cmp_gt_i32_e32 vcc, s93, v37
	v_cmp_le_i32_e64 s[8:9], v35, v114
	s_and_b64 vcc, s[8:9], vcc
	v_cndmask_b32_e32 v37, v176, v38, vcc
	v_add_u32_e32 v35, 0xffffffa9, v143
	v_subrev_u32_e32 v38, 46, v141
	v_cmp_gt_i32_e32 vcc, s93, v38
	v_cmp_le_i32_e64 s[8:9], v35, v114
	s_and_b64 vcc, s[8:9], vcc
	v_cndmask_b32_e32 v35, v176, v39, vcc
	v_add_u32_e32 v38, 0xffffffaa, v143
	v_subrev_u32_e32 v39, 47, v141
	v_cmp_gt_i32_e32 vcc, s93, v39
	v_cmp_le_i32_e64 s[8:9], v38, v114
	s_and_b64 vcc, s[8:9], vcc
	v_cndmask_b32_e32 v38, v176, v40, vcc
	v_add_u32_e32 v39, 0xffffffab, v143
	v_subrev_u32_e32 v40, 48, v141
	v_cmp_gt_i32_e32 vcc, s93, v40
	v_cmp_le_i32_e64 s[8:9], v39, v114
	s_and_b64 vcc, s[8:9], vcc
	v_cndmask_b32_e32 v39, v176, v41, vcc
	v_add_u32_e32 v40, 0xffffffb0, v143
	v_subrev_u32_e32 v41, 53, v141
	v_cmp_gt_i32_e32 vcc, s93, v41
	v_cmp_le_i32_e64 s[8:9], v40, v114
	s_and_b64 vcc, s[8:9], vcc
	v_cndmask_b32_e32 v40, v176, v42, vcc
	v_add_u32_e32 v41, 0xffffffb1, v143
	v_subrev_u32_e32 v42, 54, v141
	v_cmp_gt_i32_e32 vcc, s93, v42
	v_cmp_le_i32_e64 s[8:9], v41, v114
	s_and_b64 vcc, s[8:9], vcc
	v_cndmask_b32_e32 v41, v176, v43, vcc
	v_add_u32_e32 v42, 0xffffffb2, v143
	v_subrev_u32_e32 v43, 55, v141
	v_cmp_gt_i32_e32 vcc, s93, v43
	v_cmp_le_i32_e64 s[8:9], v42, v114
	s_and_b64 vcc, s[8:9], vcc
	v_cndmask_b32_e32 v42, v176, v44, vcc
	v_add_u32_e32 v43, 0xffffffb3, v143
	v_subrev_u32_e32 v44, 56, v141
	v_cmp_gt_i32_e32 vcc, s93, v44
	v_cmp_le_i32_e64 s[8:9], v43, v114
	s_and_b64 vcc, s[8:9], vcc
	v_cndmask_b32_e32 v43, v176, v45, vcc
	v_add_u32_e32 v44, 0xffffffb8, v143
	v_subrev_u32_e32 v45, 61, v141
	v_cmp_gt_i32_e32 vcc, s93, v45
	v_cmp_le_i32_e64 s[8:9], v44, v114
	s_and_b64 vcc, s[8:9], vcc
	v_cndmask_b32_e32 v44, v176, v46, vcc
	v_add_u32_e32 v45, 0xffffffb9, v143
	v_subrev_u32_e32 v46, 62, v141
	v_cmp_gt_i32_e32 vcc, s93, v46
	v_cmp_le_i32_e64 s[8:9], v45, v114
	s_and_b64 vcc, s[8:9], vcc
	v_cndmask_b32_e32 v45, v176, v47, vcc
	v_add_u32_e32 v46, 0xffffffba, v143
	v_subrev_u32_e32 v47, 63, v141
	v_cmp_gt_i32_e32 vcc, s93, v47
	v_cmp_le_i32_e64 s[8:9], v46, v114
	s_and_b64 vcc, s[8:9], vcc
	v_cndmask_b32_e32 v46, v176, v48, vcc
	v_add_u32_e32 v47, 0xffffffbb, v143
	v_subrev_u32_e32 v48, 64, v141
	v_max3_f32 v34, v34, v55, v36
	v_cmp_gt_i32_e32 vcc, s93, v48
	v_cmp_le_i32_e64 s[8:9], v47, v114
	v_max3_f32 v34, v34, v37, v35
	s_and_b64 vcc, s[8:9], vcc
	v_max3_f32 v34, v34, v38, v39
	v_cndmask_b32_e32 v47, v176, v49, vcc
	v_and_b32_e32 v49, 64, v172
	v_max3_f32 v34, v34, v40, v41
	v_xor_b32_e32 v48, 32, v172
	v_add_u32_e32 v49, 64, v49
	v_max3_f32 v34, v34, v42, v43
	v_cmp_lt_i32_e32 vcc, v48, v49
	v_max3_f32 v34, v34, v44, v45
	v_max3_f32 v34, v34, v46, v47
	v_cndmask_b32_e32 v48, v172, v48, vcc
	v_lshlrev_b32_e32 v48, 2, v48
	ds_bpermute_b32 v48, v48, v34
	s_waitcnt lgkmcnt(0)
	v_max3_f32 v34, v144, v34, v48
	v_cmp_neq_f32_e32 vcc, v34, v144
	s_cbranch_vccz .LBB0_326
	v_sub_f32_e32 v48, v144, v34
	v_mul_f32_e32 v48, 0x3e38aa3b, v48
	v_exp_f32_e32 v48, v48
	s_nop 0
	v_mul_f32_e32 v116, v116, v48
	v_pk_mul_f32 v[32:33], v[32:33], v[48:49] op_sel_hi:[1,0]
	v_pk_mul_f32 v[30:31], v[30:31], v[48:49] op_sel_hi:[1,0]
	v_pk_mul_f32 v[28:29], v[28:29], v[48:49] op_sel_hi:[1,0]
	v_pk_mul_f32 v[26:27], v[26:27], v[48:49] op_sel_hi:[1,0]
	v_pk_mul_f32 v[24:25], v[24:25], v[48:49] op_sel_hi:[1,0]
	v_pk_mul_f32 v[22:23], v[22:23], v[48:49] op_sel_hi:[1,0]
	v_pk_mul_f32 v[20:21], v[20:21], v[48:49] op_sel_hi:[1,0]
	v_pk_mul_f32 v[18:19], v[18:19], v[48:49] op_sel_hi:[1,0]
	v_pk_mul_f32 v[16:17], v[16:17], v[48:49] op_sel_hi:[1,0]
	v_pk_mul_f32 v[14:15], v[14:15], v[48:49] op_sel_hi:[1,0]
	v_pk_mul_f32 v[12:13], v[12:13], v[48:49] op_sel_hi:[1,0]
	v_pk_mul_f32 v[10:11], v[10:11], v[48:49] op_sel_hi:[1,0]
	v_pk_mul_f32 v[8:9], v[8:9], v[48:49] op_sel_hi:[1,0]
	v_pk_mul_f32 v[6:7], v[6:7], v[48:49] op_sel_hi:[1,0]
	v_pk_mul_f32 v[4:5], v[4:5], v[48:49] op_sel_hi:[1,0]
	v_pk_mul_f32 v[2:3], v[2:3], v[48:49] op_sel_hi:[1,0]
; DI unsigned pack2(float a, float b) { unsigned r; asm("v_cvt_pk_bf16_f32 %0, %1, %2\n\ts_nop 1" : "=v"(r) : "v"(a), "v"(b)); return r; }
; #define MFMA32(a, b, c) __builtin_amdgcn_mfma_f32_32x32x16_bf16((a), (b), (c), 0, 0, 0)
; template <int DQK, bool WIN>
; DI void attn_item(const u16* __restrict__ Qb, int ldq, const u16* __restrict__ Kb, int ldk, const u16* __restrict__ Vtb, int qb,
;                   float qscale, float sink2, const u16* __restrict__ zb, int ldz, u16* __restrict__ ob, int ldo, u16* lds) {
;     ...
;       const float nb = -mn * qscale;
;       float ps = 0.f;
; #pragma unroll
;       for (int kb = 0; kb < 2; ++kb)
; #pragma unroll
;         for (int i = 0; i < 16; ++i) { float pv = __builtin_amdgcn_exp2f(fmaf(st[kb][i], qscale, nb)); st[kb][i] = pv; ps += pv; }
;       lsum += ps;
; #pragma unroll
;       for (int kb = 0; kb < 2; ++kb)
; #pragma unroll
;         for (int s2 = 0; s2 < 2; ++s2) {
;           union { bf16x8 v; unsigned u[4]; } pf;
; #pragma unroll
;           for (int j = 0; j < 4; ++j) pf.u[j] = pack2(st[kb][8 * s2 + 2 * j], st[kb][8 * s2 + 2 * j + 1]);
; #pragma unroll
;           for (int vb = 0; vb < 2; ++vb) {
;             const bf16x8 vf = *(const bf16x8*)(vs + (vb * 32 + r) * 72 + (kb * 2 + s2) * 16 + hh * 8);
;             o[vb] = MFMA32(vf, pf.v, o[vb]);
;           }
;         }
.LBB0_326:
	ds_read_b128 v[220:223], v140 offset:27648
	ds_read_b128 v[224:227], v140 offset:32256
	ds_read_b128 v[228:231], v140 offset:32288
	ds_read_b128 v[232:235], v140 offset:27712
	ds_read_b128 v[236:239], v140 offset:32320
	ds_read_b128 v[240:243], v140 offset:27744
	v_mul_f32_e32 v48, 0xbe38aa3b, v34
	v_fmamk_f32 v49, v50, 0x3e38aa3b, v48
	v_exp_f32_e32 v49, v49
	v_fmamk_f32 v51, v51, 0x3e38aa3b, v48
	v_exp_f32_e32 v51, v51
	v_fmamk_f32 v52, v52, 0x3e38aa3b, v48
	v_exp_f32_e32 v52, v52
	v_fmamk_f32 v53, v53, 0x3e38aa3b, v48
	v_exp_f32_e32 v53, v53
	v_fmamk_f32 v62, v148, 0x3e38aa3b, v48
	v_add_f32_e32 v50, 0, v49
	v_exp_f32_e32 v62, v62
	v_fmamk_f32 v63, v147, 0x3e38aa3b, v48
	v_add_f32_e32 v50, v51, v50
	v_exp_f32_e32 v63, v63
	v_fmamk_f32 v64, v149, 0x3e38aa3b, v48
	v_add_f32_e32 v50, v52, v50
	v_exp_f32_e32 v64, v64
	v_fmamk_f32 v65, v150, 0x3e38aa3b, v48
	v_add_f32_e32 v50, v53, v50
	v_exp_f32_e32 v65, v65
	v_fmamk_f32 v143, v151, 0x3e38aa3b, v48
	v_add_f32_e32 v50, v62, v50
	v_exp_f32_e32 v143, v143
	v_fmamk_f32 v144, v145, 0x3e38aa3b, v48
	v_add_f32_e32 v50, v63, v50
	v_exp_f32_e32 v144, v144
	v_fmamk_f32 v145, v146, 0x3e38aa3b, v48
	v_add_f32_e32 v50, v64, v50
	v_exp_f32_e32 v145, v145
	v_fmamk_f32 v60, v60, 0x3e38aa3b, v48
	v_add_f32_e32 v50, v65, v50
	v_exp_f32_e32 v60, v60
	v_fmamk_f32 v61, v61, 0x3e38aa3b, v48
	v_add_f32_e32 v50, v143, v50
	v_exp_f32_e32 v61, v61
	v_fmamk_f32 v58, v58, 0x3e38aa3b, v48
	v_add_f32_e32 v50, v144, v50
	v_exp_f32_e32 v58, v58
	v_fmamk_f32 v59, v59, 0x3e38aa3b, v48
	v_add_f32_e32 v50, v145, v50
	v_exp_f32_e32 v59, v59
	v_fmamk_f32 v56, v56, 0x3e38aa3b, v48
	v_add_f32_e32 v50, v60, v50
	v_exp_f32_e32 v56, v56
	v_fmamk_f32 v57, v57, 0x3e38aa3b, v48
	v_add_f32_e32 v50, v61, v50
	v_exp_f32_e32 v57, v57
	v_fmamk_f32 v54, v54, 0x3e38aa3b, v48
	v_add_f32_e32 v50, v58, v50
	v_exp_f32_e32 v54, v54
	v_fmamk_f32 v55, v55, 0x3e38aa3b, v48
	v_add_f32_e32 v50, v59, v50
	v_exp_f32_e32 v55, v55
	v_fmamk_f32 v36, v36, 0x3e38aa3b, v48
	v_add_f32_e32 v50, v56, v50
	v_exp_f32_e32 v146, v36
	v_add_f32_e32 v50, v57, v50
	v_add_f32_e32 v50, v54, v50
	v_add_f32_e32 v50, v55, v50
	v_fmamk_f32 v37, v37, 0x3e38aa3b, v48
	v_add_f32_e32 v36, v146, v50
	v_exp_f32_e32 v50, v37
	v_fmamk_f32 v35, v35, 0x3e38aa3b, v48
	v_exp_f32_e32 v35, v35
	v_fmamk_f32 v37, v38, 0x3e38aa3b, v48
	v_exp_f32_e32 v147, v37
	v_fmamk_f32 v37, v39, 0x3e38aa3b, v48
	v_exp_f32_e32 v148, v37
	v_fmamk_f32 v37, v40, 0x3e38aa3b, v48
	v_add_f32_e32 v36, v50, v36
	v_exp_f32_e32 v149, v37
	v_fmamk_f32 v37, v41, 0x3e38aa3b, v48
	v_add_f32_e32 v36, v35, v36
	v_exp_f32_e32 v150, v37
	v_fmamk_f32 v37, v42, 0x3e38aa3b, v48
	v_add_f32_e32 v36, v147, v36
	v_exp_f32_e32 v151, v37
	v_fmamk_f32 v37, v43, 0x3e38aa3b, v48
	v_add_f32_e32 v36, v148, v36
	v_exp_f32_e32 v152, v37
	v_fmamk_f32 v37, v44, 0x3e38aa3b, v48
	v_add_f32_e32 v36, v149, v36
	v_exp_f32_e32 v153, v37
	v_fmamk_f32 v37, v45, 0x3e38aa3b, v48
	v_add_f32_e32 v36, v150, v36
	v_exp_f32_e32 v154, v37
	v_fmamk_f32 v37, v46, 0x3e38aa3b, v48
	v_add_f32_e32 v36, v151, v36
	v_exp_f32_e32 v155, v37
	v_fmac_f32_e32 v48, 0x3e38aa3b, v47
	v_add_f32_e32 v36, v152, v36
	v_exp_f32_e32 v48, v48
	v_add_f32_e32 v36, v153, v36
	ds_read_b128 v[44:47], v140 offset:27680
	v_add_f32_e32 v36, v154, v36
	v_add_f32_e32 v36, v155, v36
	v_add_f32_e32 v36, v48, v36
	v_add_f32_e32 v116, v36, v116
	v_cvt_pk_bf16_f32 v36, v49, v51
	s_nop 1
	v_cvt_pk_bf16_f32 v37, v52, v53
	s_nop 1
	v_cvt_pk_bf16_f32 v38, v62, v63
	s_nop 1
	v_cvt_pk_bf16_f32 v39, v64, v65
	s_nop 1
	s_waitcnt lgkmcnt(6)
	v_mfma_f32_32x32x16_bf16 v[18:33], v[220:223], v[36:39], v[18:33]
	s_waitcnt lgkmcnt(0)
	v_mfma_f32_32x32x16_bf16 v[2:17], v[224:227], v[36:39], v[2:17]
	v_cvt_pk_bf16_f32 v36, v143, v144
	s_nop 1
	v_cvt_pk_bf16_f32 v37, v145, v60
	s_nop 1
	v_cvt_pk_bf16_f32 v38, v61, v58
	s_nop 1
	v_cvt_pk_bf16_f32 v39, v59, v56
	s_nop 1
	v_mov_b32_e32 v144, v34
	s_waitcnt lgkmcnt(0)
	v_mfma_f32_32x32x16_bf16 v[2:17], v[228:231], v[36:39], v[2:17]
	v_mfma_f32_32x32x16_bf16 v[18:33], v[44:47], v[36:39], v[18:33]
	v_cvt_pk_bf16_f32 v36, v57, v54
	s_nop 1
	v_cvt_pk_bf16_f32 v37, v55, v146
	s_nop 1
	v_cvt_pk_bf16_f32 v38, v50, v35
	s_nop 1
	v_cvt_pk_bf16_f32 v39, v147, v148
	s_nop 1
	s_waitcnt lgkmcnt(0)
	v_mfma_f32_32x32x16_bf16 v[18:33], v[232:235], v[36:39], v[18:33]
	s_waitcnt lgkmcnt(0)
	v_mfma_f32_32x32x16_bf16 v[2:17], v[236:239], v[36:39], v[2:17]
	v_cvt_pk_bf16_f32 v36, v149, v150
	s_nop 1
	v_cvt_pk_bf16_f32 v37, v151, v152
	s_nop 1
	v_cvt_pk_bf16_f32 v38, v153, v154
	s_nop 1
	v_cvt_pk_bf16_f32 v39, v155, v48
	s_nop 1
	s_waitcnt lgkmcnt(0)
	v_mfma_f32_32x32x16_bf16 v[18:33], v[240:243], v[36:39], v[18:33]
	ds_read_b128 v[40:43], v140 offset:32352
	s_waitcnt lgkmcnt(0)
	v_mfma_f32_32x32x16_bf16 v[2:17], v[40:43], v[36:39], v[2:17]
